# K-loop LDS-DMA loads: 37 loads switched to scalar-base + 32-bit lane offset form (64-bit VALU adds removed from load segments); setprio flips deleted; plus previous edits
# speedup vs baseline: 1.0330x; 1.0330x over previous
;     __device__ __forceinline__ void prefetch(const Unit& u, int wr, int wc, int lane) const { lnfold_prefetch(vl, stats, gW, bW, u, wr, wc, lane); }
;     __device__ __forceinline__ void prefetch(const Unit& u, int wr, int wc, int lane) const { lnfold_prefetch(vl, stats, gW, bW, u, wr, wc, lane); }
; #define PG8_STAGE(bufoff, gbase, voff) do { _Pragma("unroll") for (int _i = 0; _i < 2; ++_i) \
;         __builtin_amdgcn_global_load_lds((const unsigned*)((const char*)(gbase) + (voff)[_i]), (LAS unsigned*)(lds + (bufoff) + ldsw + _i * 8192), 16, 0, 0); } while (0)
; #define PG8_LDA(dst, b, h) do { _Pragma("unroll") for (int m = 0; m < 4; ++m) _Pragma("unroll") for (int k = 0; k < 2; ++k) dst[m][k] = *(const LAS f16x8*)(lds + PG8_SA(b, h) + aoff + m * 2048 + k * 1024); } while (0)
; #define PG8_LDB(dst, b, h) do { _Pragma("unroll") for (int n = 0; n < 2; ++n) _Pragma("unroll") for (int k = 0; k < 2; ++k) dst[n][k] = *(const LAS f16x8*)(lds + PG8_SB(b, h) + boff + n * 2048 + k * 1024); } while (0)
; #define PG8_MMA(ai, bj, At, Bt) do { __builtin_amdgcn_s_setprio(1); _Pragma("unroll") for (int m = 0; m < 4; ++m) _Pragma("unroll") for (int n = 0; n < 2; ++n) _Pragma("unroll") for (int k = 0; k < 2; ++k) \
;         acc[ai][bj][m][n] = __builtin_amdgcn_mfma_f32_16x16x32_f16(Bt[n][k], At[m][k], acc[ai][bj][m][n], 0, 0, 0); __builtin_amdgcn_s_setprio(0); } while (0)
; template <class Epi>
; __device__ __forceinline__ void gemm_phase(LAS unsigned char* lds, const Gemm g0, const StaticOrder& S, const Epi& E) {
;     ...
;             const bool last = (t == nt - 2);
;             if (Epi::PREF && last) E.prefetch(cur, wr, wc, lane);
;             const char* a1 = cA + (size_t)(t + 1) * kstep;
;             const char* a2 = last ? nA : cA + (size_t)(t + 2) * kstep; const char* b2 = last ? nB : cB + (size_t)(t + 2) * kstep;
;             const char* a3 = a2 + kstep; const char* b3 = b2 + kstep;
;             PG8_LDB(B0, 0, 0); PG8_SCHED; PG8_LDA(At, 0, 0); PG8_STAGE(PG8_SA(1, 1), a1 + hstep, voffA);
;             PG8_WAIT_L(8); PG8_BAR; PG8_WAIT_L(0); PG8_MMA(0, 0, At, B0); PG8_BAR; PG8_SCHED;
;             PG8_LDB(B1, 0, 1); PG8_STAGE(PG8_SB(0, 0), b2, voffB);
;             PG8_BAR; PG8_WAIT_L(0); PG8_MMA(0, 1, At, B1); PG8_BAR;
;             PG8_LDA(At, 0, 1); PG8_STAGE(PG8_SA(0, 0), a2, voffA);
;             PG8_BAR; PG8_WAIT_L(0); PG8_MMA(1, 0, At, B0); PG8_BAR; PG8_SCHED;
.LBB0_198:
	s_add_u32 s52, s0, 0xfff80080
	s_addc_u32 s53, s1, -1
	s_and_b64 s[22:23], s[50:51], exec
	s_cselect_b32 s53, s75, s53
	s_cselect_b32 s52, s80, s52
	s_add_i32 s84, 0, 0x10000
	v_add_u32_e32 v148, s84, v214
	ds_read_b128 v[136:139], v148
	ds_read_b128 v[140:143], v148 offset:1024
	ds_read_b128 v[144:147], v148 offset:2048
	ds_read_b128 v[148:151], v148 offset:3072
	s_and_b64 s[22:23], s[50:51], exec
	s_cselect_b32 s51, s81, s25
	s_cselect_b32 s50, s82, s24
	s_add_i32 m0, s28, 0xc000
	ds_read_b128 v[152:155], v222
	ds_read_b128 v[156:159], v222 offset:1024
	ds_read_b128 v[186:189], v222 offset:2048
	ds_read_b128 v[190:193], v222 offset:3072
	ds_read_b128 v[194:197], v222 offset:4096
	ds_read_b128 v[198:201], v222 offset:5120
	ds_read_b128 v[202:205], v222 offset:6144
	ds_read_b128 v[206:209], v222 offset:7168
	global_load_lds_dwordx4 v184, s[0:1]
	s_add_i32 m0, s28, 0xe000
	s_nop 0
	global_load_lds_dwordx4 v182, s[0:1]
	s_waitcnt lgkmcnt(8)
	s_barrier
	s_waitcnt lgkmcnt(0)
	s_waitcnt lgkmcnt(0)
	v_mfma_f32_16x16x32_f16 v[126:129], v[136:139], v[152:155], v[126:129]
	v_mfma_f32_16x16x32_f16 v[122:125], v[144:147], v[152:155], v[122:125]
	v_mfma_f32_16x16x32_f16 v[118:121], v[136:139], v[186:189], v[118:121]
	v_mfma_f32_16x16x32_f16 v[110:113], v[144:147], v[186:189], v[110:113]
	v_mfma_f32_16x16x32_f16 v[102:105], v[136:139], v[194:197], v[102:105]
	v_mfma_f32_16x16x32_f16 v[98:101], v[144:147], v[194:197], v[98:101]
	v_mfma_f32_16x16x32_f16 v[86:89], v[136:139], v[202:205], v[86:89]
	v_mfma_f32_16x16x32_f16 v[82:85], v[144:147], v[202:205], v[82:85]
	v_mfma_f32_16x16x32_f16 v[126:129], v[140:143], v[156:159], v[126:129]
	v_mfma_f32_16x16x32_f16 v[122:125], v[148:151], v[156:159], v[122:125]
	v_mfma_f32_16x16x32_f16 v[118:121], v[140:143], v[190:193], v[118:121]
	v_mfma_f32_16x16x32_f16 v[110:113], v[148:151], v[190:193], v[110:113]
	v_mfma_f32_16x16x32_f16 v[102:105], v[140:143], v[198:201], v[102:105]
	v_mfma_f32_16x16x32_f16 v[98:101], v[148:151], v[198:201], v[98:101]
	v_mfma_f32_16x16x32_f16 v[86:89], v[140:143], v[206:209], v[86:89]
	v_mfma_f32_16x16x32_f16 v[82:85], v[148:151], v[206:209], v[82:85]
	s_barrier
	s_add_i32 s85, 0, 0x14000
	v_add_u32_e32 v160, s85, v214
	s_add_i32 s22, s84, s19
	ds_read_b128 v[210:213], v160
	ds_read_b128 v[234:237], v160 offset:1024
	ds_read_b128 v[238:241], v160 offset:2048
	ds_read_b128 v[242:245], v160 offset:3072
	v_lshl_add_u64 v[160:161], s[50:51], 0, v[178:179]
	s_mov_b32 m0, s22
	v_lshl_add_u64 v[162:163], s[50:51], 0, v[174:175]
	global_load_lds_dwordx4 v[160:161], off
	s_add_i32 m0, s22, 0x2000
	s_nop 0
	global_load_lds_dwordx4 v[162:163], off
	s_barrier
	s_waitcnt lgkmcnt(0)
	s_waitcnt lgkmcnt(0)
	v_mfma_f32_16x16x32_f16 v[114:117], v[210:213], v[152:155], v[114:117]
	v_mfma_f32_16x16x32_f16 v[106:109], v[238:241], v[152:155], v[106:109]
	v_mfma_f32_16x16x32_f16 v[94:97], v[210:213], v[186:189], v[94:97]
	v_mfma_f32_16x16x32_f16 v[90:93], v[238:241], v[186:189], v[90:93]
	v_mfma_f32_16x16x32_f16 v[78:81], v[210:213], v[194:197], v[78:81]
	v_mfma_f32_16x16x32_f16 v[74:77], v[238:241], v[194:197], v[74:77]
	v_mfma_f32_16x16x32_f16 v[70:73], v[210:213], v[202:205], v[70:73]
	v_mfma_f32_16x16x32_f16 v[66:69], v[238:241], v[202:205], v[66:69]
	v_mfma_f32_16x16x32_f16 v[114:117], v[234:237], v[156:159], v[114:117]
	v_mfma_f32_16x16x32_f16 v[106:109], v[242:245], v[156:159], v[106:109]
	v_mfma_f32_16x16x32_f16 v[94:97], v[234:237], v[190:193], v[94:97]
	v_mfma_f32_16x16x32_f16 v[90:93], v[242:245], v[190:193], v[90:93]
	v_mfma_f32_16x16x32_f16 v[78:81], v[234:237], v[198:201], v[78:81]
	v_mfma_f32_16x16x32_f16 v[74:77], v[242:245], v[198:201], v[74:77]
	v_mfma_f32_16x16x32_f16 v[70:73], v[234:237], v[206:209], v[70:73]
	v_mfma_f32_16x16x32_f16 v[66:69], v[242:245], v[206:209], v[66:69]
	s_mov_b32 m0, s28
	v_lshl_add_u64 v[164:165], s[52:53], 0, v[180:181]
	s_barrier
	ds_read_b128 v[152:155], v222 offset:16384
	ds_read_b128 v[156:159], v222 offset:17408
	ds_read_b128 v[186:189], v222 offset:18432
	ds_read_b128 v[190:193], v222 offset:19456
	ds_read_b128 v[194:197], v222 offset:20480
	ds_read_b128 v[198:201], v222 offset:21504
	ds_read_b128 v[202:205], v222 offset:22528
	ds_read_b128 v[206:209], v222 offset:23552
	global_load_lds_dwordx4 v[164:165], off
	v_lshl_add_u64 v[170:171], s[52:53], 0, v[176:177]
	s_mov_b32 m0, s29
	s_nop 0
	global_load_lds_dwordx4 v[170:171], off
	s_barrier
	s_waitcnt lgkmcnt(0)
	s_waitcnt lgkmcnt(0)
	v_mfma_f32_16x16x32_f16 v[62:65], v[136:139], v[152:155], v[62:65]
	v_mfma_f32_16x16x32_f16 v[58:61], v[144:147], v[152:155], v[58:61]
	v_mfma_f32_16x16x32_f16 v[54:57], v[136:139], v[186:189], v[54:57]
	v_mfma_f32_16x16x32_f16 v[50:53], v[144:147], v[186:189], v[50:53]
	v_mfma_f32_16x16x32_f16 v[38:41], v[136:139], v[194:197], v[38:41]
	v_mfma_f32_16x16x32_f16 v[30:33], v[144:147], v[194:197], v[30:33]
	v_mfma_f32_16x16x32_f16 v[22:25], v[136:139], v[202:205], v[22:25]
	v_mfma_f32_16x16x32_f16 v[18:21], v[144:147], v[202:205], v[18:21]
	v_mfma_f32_16x16x32_f16 v[62:65], v[140:143], v[156:159], v[62:65]
	v_mfma_f32_16x16x32_f16 v[58:61], v[148:151], v[156:159], v[58:61]
	v_mfma_f32_16x16x32_f16 v[54:57], v[140:143], v[190:193], v[54:57]
	v_mfma_f32_16x16x32_f16 v[50:53], v[148:151], v[190:193], v[50:53]
	v_mfma_f32_16x16x32_f16 v[38:41], v[140:143], v[198:201], v[38:41]
	v_mfma_f32_16x16x32_f16 v[30:33], v[148:151], v[198:201], v[30:33]
	v_mfma_f32_16x16x32_f16 v[22:25], v[140:143], v[206:209], v[22:25]
	v_mfma_f32_16x16x32_f16 v[18:21], v[148:151], v[206:209], v[18:21]
	s_barrier
; #define PG8_STAGE(bufoff, gbase, voff) do { _Pragma("unroll") for (int _i = 0; _i < 2; ++_i) \
;         __builtin_amdgcn_global_load_lds((const unsigned*)((const char*)(gbase) + (voff)[_i]), (LAS unsigned*)(lds + (bufoff) + ldsw + _i * 8192), 16, 0, 0); } while (0)
; #define PG8_LDA(dst, b, h) do { _Pragma("unroll") for (int m = 0; m < 4; ++m) _Pragma("unroll") for (int k = 0; k < 2; ++k) dst[m][k] = *(const LAS f16x8*)(lds + PG8_SA(b, h) + aoff + m * 2048 + k * 1024); } while (0)
; #define PG8_LDB(dst, b, h) do { _Pragma("unroll") for (int n = 0; n < 2; ++n) _Pragma("unroll") for (int k = 0; k < 2; ++k) dst[n][k] = *(const LAS f16x8*)(lds + PG8_SB(b, h) + boff + n * 2048 + k * 1024); } while (0)
; #define PG8_MMA(ai, bj, At, Bt) do { __builtin_amdgcn_s_setprio(1); _Pragma("unroll") for (int m = 0; m < 4; ++m) _Pragma("unroll") for (int n = 0; n < 2; ++n) _Pragma("unroll") for (int k = 0; k < 2; ++k) \
;         acc[ai][bj][m][n] = __builtin_amdgcn_mfma_f32_16x16x32_f16(Bt[n][k], At[m][k], acc[ai][bj][m][n], 0, 0, 0); __builtin_amdgcn_s_setprio(0); } while (0)
; #define PG8_WAIT_V(n) asm volatile("s_waitcnt vmcnt(" #n ")" ::: "memory")
; #define PG8_WAIT_L(n) asm volatile("s_waitcnt lgkmcnt(" #n ")" ::: "memory")
; #define PG8_BAR __builtin_amdgcn_s_barrier()
; #define PG8_SCHED __builtin_amdgcn_sched_barrier(0)
; template <class Epi>
; __device__ __forceinline__ void gemm_phase(LAS unsigned char* lds, const Gemm g0, const StaticOrder& S, const Epi& E) {
;     ...
;             PG8_STAGE(PG8_SB(0, 1), b2 + hstep, voffB);
;             PG8_WAIT_V(6); PG8_BAR; PG8_MMA(1, 1, At, B1); PG8_BAR;
;             PG8_LDB(B0, 1, 0); PG8_SCHED; PG8_LDA(At, 1, 0); PG8_STAGE(PG8_SA(0, 1), a2 + hstep, voffA);
;             PG8_WAIT_L(8); PG8_BAR; PG8_WAIT_L(0); PG8_MMA(0, 0, At, B0); PG8_BAR; PG8_SCHED;
;             PG8_LDB(B1, 1, 1); PG8_STAGE(PG8_SB(1, 0), b3, voffB);
;             PG8_BAR; PG8_WAIT_L(0); PG8_MMA(0, 1, At, B1); PG8_BAR;
	s_add_u32 s22, s50, 0x80000
	s_addc_u32 s23, s51, 0
	s_add_i32 s84, s85, s19
	s_mov_b32 m0, s84
	s_nop 0
	global_load_lds_dwordx4 v178, s[22:23]
	s_add_i32 m0, s84, 0x2000
	s_nop 0
	global_load_lds_dwordx4 v174, s[22:23]
	s_waitcnt vmcnt(6)
	s_barrier
	v_mfma_f32_16x16x32_f16 v[46:49], v[210:213], v[152:155], v[46:49]
	v_mfma_f32_16x16x32_f16 v[42:45], v[238:241], v[152:155], v[42:45]
	v_mfma_f32_16x16x32_f16 v[34:37], v[210:213], v[186:189], v[34:37]
	v_mfma_f32_16x16x32_f16 v[26:29], v[238:241], v[186:189], v[26:29]
	v_mfma_f32_16x16x32_f16 v[14:17], v[210:213], v[194:197], v[14:17]
	v_mfma_f32_16x16x32_f16 v[10:13], v[238:241], v[194:197], v[10:13]
	v_mfma_f32_16x16x32_f16 v[6:9], v[210:213], v[202:205], v[6:9]
	v_mfma_f32_16x16x32_f16 v[2:5], v[238:241], v[202:205], v[2:5]
	v_mfma_f32_16x16x32_f16 v[46:49], v[234:237], v[156:159], v[46:49]
	v_mfma_f32_16x16x32_f16 v[42:45], v[242:245], v[156:159], v[42:45]
	v_mfma_f32_16x16x32_f16 v[34:37], v[234:237], v[190:193], v[34:37]
	v_mfma_f32_16x16x32_f16 v[26:29], v[242:245], v[190:193], v[26:29]
	v_mfma_f32_16x16x32_f16 v[14:17], v[234:237], v[198:201], v[14:17]
	v_mfma_f32_16x16x32_f16 v[10:13], v[242:245], v[198:201], v[10:13]
	v_mfma_f32_16x16x32_f16 v[6:9], v[234:237], v[206:209], v[6:9]
	v_mfma_f32_16x16x32_f16 v[2:5], v[242:245], v[206:209], v[2:5]
	s_add_i32 s84, 0, 0x18000
	v_add_u32_e32 v148, s84, v214
	s_barrier
	ds_read_b128 v[136:139], v148
	ds_read_b128 v[140:143], v148 offset:1024
	ds_read_b128 v[144:147], v148 offset:2048
	ds_read_b128 v[148:151], v148 offset:3072
	s_add_u32 s22, s52, 0x80000
	s_addc_u32 s23, s53, 0
	s_mov_b32 m0, s31
	ds_read_b128 v[152:155], v222 offset:32768
	ds_read_b128 v[156:159], v222 offset:33792
	ds_read_b128 v[186:189], v222 offset:34816
	ds_read_b128 v[190:193], v222 offset:35840
	ds_read_b128 v[194:197], v222 offset:36864
	ds_read_b128 v[198:201], v222 offset:37888
	ds_read_b128 v[202:205], v222 offset:38912
	ds_read_b128 v[206:209], v222 offset:39936
	global_load_lds_dwordx4 v180, s[22:23]
	s_mov_b32 m0, s58
	s_nop 0
	global_load_lds_dwordx4 v176, s[22:23]
	s_waitcnt lgkmcnt(8)
	s_barrier
	s_waitcnt lgkmcnt(0)
	s_waitcnt lgkmcnt(0)
	v_mfma_f32_16x16x32_f16 v[126:129], v[136:139], v[152:155], v[126:129]
	v_mfma_f32_16x16x32_f16 v[122:125], v[144:147], v[152:155], v[122:125]
	v_mfma_f32_16x16x32_f16 v[118:121], v[136:139], v[186:189], v[118:121]
	v_mfma_f32_16x16x32_f16 v[110:113], v[144:147], v[186:189], v[110:113]
	v_mfma_f32_16x16x32_f16 v[102:105], v[136:139], v[194:197], v[102:105]
	v_mfma_f32_16x16x32_f16 v[98:101], v[144:147], v[194:197], v[98:101]
	v_mfma_f32_16x16x32_f16 v[86:89], v[136:139], v[202:205], v[86:89]
	v_mfma_f32_16x16x32_f16 v[82:85], v[144:147], v[202:205], v[82:85]
	v_mfma_f32_16x16x32_f16 v[126:129], v[140:143], v[156:159], v[126:129]
	v_mfma_f32_16x16x32_f16 v[122:125], v[148:151], v[156:159], v[122:125]
	v_mfma_f32_16x16x32_f16 v[118:121], v[140:143], v[190:193], v[118:121]
	v_mfma_f32_16x16x32_f16 v[110:113], v[148:151], v[190:193], v[110:113]
	v_mfma_f32_16x16x32_f16 v[102:105], v[140:143], v[198:201], v[102:105]
	v_mfma_f32_16x16x32_f16 v[98:101], v[148:151], v[198:201], v[98:101]
	v_mfma_f32_16x16x32_f16 v[86:89], v[140:143], v[206:209], v[86:89]
	v_mfma_f32_16x16x32_f16 v[82:85], v[148:151], v[206:209], v[82:85]
	s_barrier
	s_add_i32 s52, 0, 0x1c000
	s_add_i32 s22, s84, s19
	v_add_u32_e32 v172, s52, v214
	v_lshl_add_u64 v[160:161], v[160:161], 0, s[64:65]
	s_mov_b32 m0, s22
	ds_read_b128 v[210:213], v172
	ds_read_b128 v[234:237], v172 offset:1024
	ds_read_b128 v[238:241], v172 offset:2048
	ds_read_b128 v[242:245], v172 offset:3072
	global_load_lds_dwordx4 v[160:161], off
	v_lshl_add_u64 v[160:161], v[162:163], 0, s[64:65]
	s_add_i32 m0, s22, 0x2000
	s_nop 0
	global_load_lds_dwordx4 v[160:161], off
	s_barrier
; #define PG8_STAGE(bufoff, gbase, voff) do { _Pragma("unroll") for (int _i = 0; _i < 2; ++_i) \
;         __builtin_amdgcn_global_load_lds((const unsigned*)((const char*)(gbase) + (voff)[_i]), (LAS unsigned*)(lds + (bufoff) + ldsw + _i * 8192), 16, 0, 0); } while (0)
; #define PG8_LDA(dst, b, h) do { _Pragma("unroll") for (int m = 0; m < 4; ++m) _Pragma("unroll") for (int k = 0; k < 2; ++k) dst[m][k] = *(const LAS f16x8*)(lds + PG8_SA(b, h) + aoff + m * 2048 + k * 1024); } while (0)
; #define PG8_MMA(ai, bj, At, Bt) do { __builtin_amdgcn_s_setprio(1); _Pragma("unroll") for (int m = 0; m < 4; ++m) _Pragma("unroll") for (int n = 0; n < 2; ++n) _Pragma("unroll") for (int k = 0; k < 2; ++k) \
;         acc[ai][bj][m][n] = __builtin_amdgcn_mfma_f32_16x16x32_f16(Bt[n][k], At[m][k], acc[ai][bj][m][n], 0, 0, 0); __builtin_amdgcn_s_setprio(0); } while (0)
; #define PG8_WAIT_V(n) asm volatile("s_waitcnt vmcnt(" #n ")" ::: "memory")
; #define PG8_WAIT_L(n) asm volatile("s_waitcnt lgkmcnt(" #n ")" ::: "memory")
; #define PG8_BAR __builtin_amdgcn_s_barrier()
; #define PG8_SCHED __builtin_amdgcn_sched_barrier(0)
; template <class Epi>
; __device__ __forceinline__ void gemm_phase(LAS unsigned char* lds, const Gemm g0, const StaticOrder& S, const Epi& E) {
;     ...
;             PG8_LDA(At, 1, 1); PG8_STAGE(PG8_SA(1, 0), a3, voffA);
;             PG8_BAR; PG8_WAIT_L(0); PG8_MMA(1, 0, At, B0); PG8_BAR; PG8_SCHED;
;             PG8_STAGE(PG8_SB(1, 1), b3 + hstep, voffB);
;             PG8_WAIT_V(6); PG8_BAR; PG8_MMA(1, 1, At, B1); PG8_BAR;
;         }
	s_waitcnt lgkmcnt(0)
	s_waitcnt lgkmcnt(0)
	v_mfma_f32_16x16x32_f16 v[114:117], v[210:213], v[152:155], v[114:117]
	v_mfma_f32_16x16x32_f16 v[106:109], v[238:241], v[152:155], v[106:109]
	v_mfma_f32_16x16x32_f16 v[94:97], v[210:213], v[186:189], v[94:97]
	v_mfma_f32_16x16x32_f16 v[90:93], v[238:241], v[186:189], v[90:93]
	v_mfma_f32_16x16x32_f16 v[78:81], v[210:213], v[194:197], v[78:81]
	v_mfma_f32_16x16x32_f16 v[74:77], v[238:241], v[194:197], v[74:77]
	v_mfma_f32_16x16x32_f16 v[70:73], v[210:213], v[202:205], v[70:73]
	v_mfma_f32_16x16x32_f16 v[66:69], v[238:241], v[202:205], v[66:69]
	v_mfma_f32_16x16x32_f16 v[114:117], v[234:237], v[156:159], v[114:117]
	v_mfma_f32_16x16x32_f16 v[106:109], v[242:245], v[156:159], v[106:109]
	v_mfma_f32_16x16x32_f16 v[94:97], v[234:237], v[190:193], v[94:97]
	v_mfma_f32_16x16x32_f16 v[90:93], v[242:245], v[190:193], v[90:93]
	v_mfma_f32_16x16x32_f16 v[78:81], v[234:237], v[198:201], v[78:81]
	v_mfma_f32_16x16x32_f16 v[74:77], v[242:245], v[198:201], v[74:77]
	v_mfma_f32_16x16x32_f16 v[70:73], v[234:237], v[206:209], v[70:73]
	v_mfma_f32_16x16x32_f16 v[66:69], v[242:245], v[206:209], v[66:69]
	s_mov_b32 m0, s59
	v_lshl_add_u64 v[160:161], v[164:165], 0, s[64:65]
	s_barrier
	ds_read_b128 v[152:155], v222 offset:49152
	ds_read_b128 v[156:159], v222 offset:50176
	ds_read_b128 v[186:189], v222 offset:51200
	ds_read_b128 v[190:193], v222 offset:52224
	ds_read_b128 v[194:197], v222 offset:53248
	ds_read_b128 v[198:201], v222 offset:54272
	ds_read_b128 v[202:205], v222 offset:55296
	ds_read_b128 v[206:209], v222 offset:56320
	global_load_lds_dwordx4 v[160:161], off
	v_lshl_add_u64 v[160:161], v[170:171], 0, s[64:65]
	s_mov_b32 m0, s61
	s_nop 0
	global_load_lds_dwordx4 v[160:161], off
	s_barrier
	s_waitcnt lgkmcnt(0)
	s_waitcnt lgkmcnt(0)
	v_mfma_f32_16x16x32_f16 v[62:65], v[136:139], v[152:155], v[62:65]
	v_mfma_f32_16x16x32_f16 v[58:61], v[144:147], v[152:155], v[58:61]
	v_mfma_f32_16x16x32_f16 v[54:57], v[136:139], v[186:189], v[54:57]
	v_mfma_f32_16x16x32_f16 v[50:53], v[144:147], v[186:189], v[50:53]
	v_mfma_f32_16x16x32_f16 v[38:41], v[136:139], v[194:197], v[38:41]
	v_mfma_f32_16x16x32_f16 v[30:33], v[144:147], v[194:197], v[30:33]
	v_mfma_f32_16x16x32_f16 v[22:25], v[136:139], v[202:205], v[22:25]
	v_mfma_f32_16x16x32_f16 v[18:21], v[144:147], v[202:205], v[18:21]
	v_mfma_f32_16x16x32_f16 v[62:65], v[140:143], v[156:159], v[62:65]
	v_mfma_f32_16x16x32_f16 v[58:61], v[148:151], v[156:159], v[58:61]
	v_mfma_f32_16x16x32_f16 v[54:57], v[140:143], v[190:193], v[54:57]
	v_mfma_f32_16x16x32_f16 v[50:53], v[148:151], v[190:193], v[50:53]
	v_mfma_f32_16x16x32_f16 v[38:41], v[140:143], v[198:201], v[38:41]
	v_mfma_f32_16x16x32_f16 v[30:33], v[148:151], v[198:201], v[30:33]
	v_mfma_f32_16x16x32_f16 v[22:25], v[140:143], v[206:209], v[22:25]
	v_mfma_f32_16x16x32_f16 v[18:21], v[148:151], v[206:209], v[18:21]
	s_barrier
	s_add_u32 s22, s50, 0x80080
	s_addc_u32 s23, s51, 0
	s_add_i32 s50, s52, s19
	s_mov_b32 m0, s50
	s_nop 0
	global_load_lds_dwordx4 v178, s[22:23]
	v_lshl_add_u64 v[136:137], s[22:23], 0, v[174:175]
	s_add_i32 m0, s50, 0x2000
	s_nop 0
	global_load_lds_dwordx4 v[136:137], off
	s_waitcnt vmcnt(6)
	s_barrier
	v_mfma_f32_16x16x32_f16 v[46:49], v[210:213], v[152:155], v[46:49]
	v_mfma_f32_16x16x32_f16 v[42:45], v[238:241], v[152:155], v[42:45]
	v_mfma_f32_16x16x32_f16 v[34:37], v[210:213], v[186:189], v[34:37]
	v_mfma_f32_16x16x32_f16 v[26:29], v[238:241], v[186:189], v[26:29]
	v_mfma_f32_16x16x32_f16 v[14:17], v[210:213], v[194:197], v[14:17]
	v_mfma_f32_16x16x32_f16 v[10:13], v[238:241], v[194:197], v[10:13]
	v_mfma_f32_16x16x32_f16 v[6:9], v[210:213], v[202:205], v[6:9]
	v_mfma_f32_16x16x32_f16 v[2:5], v[238:241], v[202:205], v[2:5]
	v_mfma_f32_16x16x32_f16 v[46:49], v[234:237], v[156:159], v[46:49]
	v_mfma_f32_16x16x32_f16 v[42:45], v[242:245], v[156:159], v[42:45]
	v_mfma_f32_16x16x32_f16 v[34:37], v[234:237], v[190:193], v[34:37]
	v_mfma_f32_16x16x32_f16 v[26:29], v[242:245], v[190:193], v[26:29]
	v_mfma_f32_16x16x32_f16 v[14:17], v[234:237], v[198:201], v[14:17]
	v_mfma_f32_16x16x32_f16 v[10:13], v[242:245], v[198:201], v[10:13]
	v_mfma_f32_16x16x32_f16 v[6:9], v[234:237], v[206:209], v[6:9]
	v_mfma_f32_16x16x32_f16 v[2:5], v[242:245], v[206:209], v[2:5]
	s_add_i32 s83, s83, 2
	s_add_u32 s24, s24, 0x100
	s_addc_u32 s25, s25, 0
	s_add_u32 s0, s0, 0x100
	s_addc_u32 s1, s1, 0
	s_cmp_gt_u32 s83, 29
	s_barrier
	s_cbranch_scc1 .LBB0_201

;     __device__ __forceinline__ void prefetch(const Unit& u, int wr, int wc, int lane) const { lnfold_prefetch(vl, stats, gW, bW, u, wr, wc, lane); }
;     __device__ __forceinline__ void prefetch(const Unit& u, int wr, int wc, int lane) const { lnfold_prefetch(vl, stats, gW, bW, u, wr, wc, lane); }
; #define PG8_STAGE(bufoff, gbase, voff) do { _Pragma("unroll") for (int _i = 0; _i < 2; ++_i) \
;         __builtin_amdgcn_global_load_lds((const unsigned*)((const char*)(gbase) + (voff)[_i]), (LAS unsigned*)(lds + (bufoff) + ldsw + _i * 8192), 16, 0, 0); } while (0)
; #define PG8_LDA(dst, b, h) do { _Pragma("unroll") for (int m = 0; m < 4; ++m) _Pragma("unroll") for (int k = 0; k < 2; ++k) dst[m][k] = *(const LAS f16x8*)(lds + PG8_SA(b, h) + aoff + m * 2048 + k * 1024); } while (0)
; #define PG8_LDB(dst, b, h) do { _Pragma("unroll") for (int n = 0; n < 2; ++n) _Pragma("unroll") for (int k = 0; k < 2; ++k) dst[n][k] = *(const LAS f16x8*)(lds + PG8_SB(b, h) + boff + n * 2048 + k * 1024); } while (0)
; #define PG8_WAIT_V(n) asm volatile("s_waitcnt vmcnt(" #n ")" ::: "memory")
; #define PG8_WAIT_L(n) asm volatile("s_waitcnt lgkmcnt(" #n ")" ::: "memory")
; #define PG8_BAR __builtin_amdgcn_s_barrier()
; template <class Epi>
; __device__ __forceinline__ void gemm_phase(LAS unsigned char* lds, const Gemm g0, const StaticOrder& S, const Epi& E) {
;     ...
;             const bool last = (t == nt - 2);
;             if (Epi::PREF && last) E.prefetch(cur, wr, wc, lane);
;             const char* a1 = cA + (size_t)(t + 1) * kstep;
;             const char* a2 = last ? nA : cA + (size_t)(t + 2) * kstep; const char* b2 = last ? nB : cB + (size_t)(t + 2) * kstep;
;             const char* a3 = a2 + kstep; const char* b3 = b2 + kstep;
;             PG8_LDB(B0, 0, 0); PG8_SCHED; PG8_LDA(At, 0, 0); PG8_STAGE(PG8_SA(1, 1), a1 + hstep, voffA);
;             PG8_WAIT_L(8); PG8_BAR; PG8_WAIT_L(0); PG8_MMA(0, 0, At, B0); PG8_BAR; PG8_SCHED;
;             PG8_LDB(B1, 0, 1); PG8_STAGE(PG8_SB(0, 0), b2, voffB);
;             PG8_BAR; PG8_WAIT_L(0); PG8_MMA(0, 1, At, B1); PG8_BAR;
;             PG8_LDA(At, 0, 1); PG8_STAGE(PG8_SA(0, 0), a2, voffA);
;             PG8_BAR; PG8_WAIT_L(0); PG8_MMA(1, 0, At, B0); PG8_BAR; PG8_SCHED;
;             PG8_STAGE(PG8_SB(0, 1), b2 + hstep, voffB);
;             PG8_WAIT_V(6); PG8_BAR; PG8_MMA(1, 1, At, B1); PG8_BAR;
.LBB0_302:
	s_add_u32 s22, s6, 0xfff80080
	s_addc_u32 s23, s7, -1
	s_add_i32 s59, 0, 0x10000
	v_add_u32_e32 v146, s59, v148
	ds_read_b128 v[142:145], v146
	ds_read_b128 v[152:155], v146 offset:1024
	ds_read_b128 v[156:159], v146 offset:2048
	ds_read_b128 v[174:177], v146 offset:3072
	s_cmp_eq_u32 s58, 28
	s_cselect_b32 s37, s15, s23
	s_cselect_b32 s36, s52, s22
	s_cselect_b32 s35, s13, s53
	s_cselect_b32 s34, s24, s25
	s_add_i32 m0, s28, 0xc000
	ds_read_b128 v[178:181], v150
	ds_read_b128 v[182:185], v150 offset:1024
	ds_read_b128 v[186:189], v150 offset:2048
	ds_read_b128 v[190:193], v150 offset:3072
	ds_read_b128 v[194:197], v150 offset:4096
	ds_read_b128 v[198:201], v150 offset:5120
	ds_read_b128 v[202:205], v150 offset:6144
	ds_read_b128 v[206:209], v150 offset:7168
	global_load_lds_dwordx4 v140, s[6:7]
	s_add_i32 m0, s28, 0xe000
	s_nop 0
	global_load_lds_dwordx4 v138, s[6:7]
	s_waitcnt lgkmcnt(8)
	s_barrier
	s_waitcnt lgkmcnt(0)
	s_waitcnt lgkmcnt(0)
	v_mfma_f32_16x16x32_f16 v[126:129], v[142:145], v[178:181], v[126:129]
	v_mfma_f32_16x16x32_f16 v[122:125], v[156:159], v[178:181], v[122:125]
	v_mfma_f32_16x16x32_f16 v[110:113], v[142:145], v[186:189], v[110:113]
	v_mfma_f32_16x16x32_f16 v[106:109], v[156:159], v[186:189], v[106:109]
	v_mfma_f32_16x16x32_f16 v[94:97], v[142:145], v[194:197], v[94:97]
	v_mfma_f32_16x16x32_f16 v[90:93], v[156:159], v[194:197], v[90:93]
	v_mfma_f32_16x16x32_f16 v[78:81], v[142:145], v[202:205], v[78:81]
	v_mfma_f32_16x16x32_f16 v[74:77], v[156:159], v[202:205], v[74:77]
	v_mfma_f32_16x16x32_f16 v[126:129], v[152:155], v[182:185], v[126:129]
	v_mfma_f32_16x16x32_f16 v[122:125], v[174:177], v[182:185], v[122:125]
	v_mfma_f32_16x16x32_f16 v[110:113], v[152:155], v[190:193], v[110:113]
	v_mfma_f32_16x16x32_f16 v[106:109], v[174:177], v[190:193], v[106:109]
	v_mfma_f32_16x16x32_f16 v[94:97], v[152:155], v[198:201], v[94:97]
	v_mfma_f32_16x16x32_f16 v[90:93], v[174:177], v[198:201], v[90:93]
	v_mfma_f32_16x16x32_f16 v[78:81], v[152:155], v[206:209], v[78:81]
	v_mfma_f32_16x16x32_f16 v[74:77], v[174:177], v[206:209], v[74:77]
	s_barrier
	s_add_i32 s61, 0, 0x14000
	v_add_u32_e32 v146, s61, v148
	s_add_i32 s22, s59, s19
	ds_read_b128 v[210:213], v146
	ds_read_b128 v[234:237], v146 offset:1024
	ds_read_b128 v[238:241], v146 offset:2048
	ds_read_b128 v[242:245], v146 offset:3072
	v_lshl_add_u64 v[146:147], s[34:35], 0, v[134:135]
	s_mov_b32 m0, s22
	v_lshl_add_u64 v[160:161], s[34:35], 0, v[130:131]
	global_load_lds_dwordx4 v[146:147], off
	s_add_i32 m0, s22, 0x2000
	s_nop 0
	global_load_lds_dwordx4 v[160:161], off
	s_barrier
	s_waitcnt lgkmcnt(0)
	s_waitcnt lgkmcnt(0)
	v_mfma_f32_16x16x32_f16 v[118:121], v[210:213], v[178:181], v[118:121]
	v_mfma_f32_16x16x32_f16 v[114:117], v[238:241], v[178:181], v[114:117]
	v_mfma_f32_16x16x32_f16 v[102:105], v[210:213], v[186:189], v[102:105]
	v_mfma_f32_16x16x32_f16 v[98:101], v[238:241], v[186:189], v[98:101]
	v_mfma_f32_16x16x32_f16 v[86:89], v[210:213], v[194:197], v[86:89]
	v_mfma_f32_16x16x32_f16 v[82:85], v[238:241], v[194:197], v[82:85]
	v_mfma_f32_16x16x32_f16 v[70:73], v[210:213], v[202:205], v[70:73]
	v_mfma_f32_16x16x32_f16 v[66:69], v[238:241], v[202:205], v[66:69]
	v_mfma_f32_16x16x32_f16 v[118:121], v[234:237], v[182:185], v[118:121]
	v_mfma_f32_16x16x32_f16 v[114:117], v[242:245], v[182:185], v[114:117]
	v_mfma_f32_16x16x32_f16 v[102:105], v[234:237], v[190:193], v[102:105]
	v_mfma_f32_16x16x32_f16 v[98:101], v[242:245], v[190:193], v[98:101]
	v_mfma_f32_16x16x32_f16 v[86:89], v[234:237], v[198:201], v[86:89]
	v_mfma_f32_16x16x32_f16 v[82:85], v[242:245], v[198:201], v[82:85]
	v_mfma_f32_16x16x32_f16 v[70:73], v[234:237], v[206:209], v[70:73]
	v_mfma_f32_16x16x32_f16 v[66:69], v[242:245], v[206:209], v[66:69]
	s_mov_b32 m0, s28
	v_lshl_add_u64 v[162:163], s[36:37], 0, v[136:137]
	s_barrier
	ds_read_b128 v[178:181], v150 offset:16384
	ds_read_b128 v[182:185], v150 offset:17408
	ds_read_b128 v[186:189], v150 offset:18432
	ds_read_b128 v[190:193], v150 offset:19456
	ds_read_b128 v[194:197], v150 offset:20480
	ds_read_b128 v[198:201], v150 offset:21504
	ds_read_b128 v[202:205], v150 offset:22528
	ds_read_b128 v[206:209], v150 offset:23552
	global_load_lds_dwordx4 v[162:163], off
	v_lshl_add_u64 v[164:165], s[36:37], 0, v[132:133]
	s_mov_b32 m0, s29
	s_nop 0
	global_load_lds_dwordx4 v[164:165], off
	s_barrier
	s_waitcnt lgkmcnt(0)
	s_waitcnt lgkmcnt(0)
	v_mfma_f32_16x16x32_f16 v[62:65], v[142:145], v[178:181], v[62:65]
	v_mfma_f32_16x16x32_f16 v[58:61], v[156:159], v[178:181], v[58:61]
	v_mfma_f32_16x16x32_f16 v[46:49], v[142:145], v[186:189], v[46:49]
	v_mfma_f32_16x16x32_f16 v[42:45], v[156:159], v[186:189], v[42:45]
	v_mfma_f32_16x16x32_f16 v[30:33], v[142:145], v[194:197], v[30:33]
	v_mfma_f32_16x16x32_f16 v[26:29], v[156:159], v[194:197], v[26:29]
	v_mfma_f32_16x16x32_f16 v[14:17], v[142:145], v[202:205], v[14:17]
	v_mfma_f32_16x16x32_f16 v[10:13], v[156:159], v[202:205], v[10:13]
	v_mfma_f32_16x16x32_f16 v[62:65], v[152:155], v[182:185], v[62:65]
	v_mfma_f32_16x16x32_f16 v[58:61], v[174:177], v[182:185], v[58:61]
	v_mfma_f32_16x16x32_f16 v[46:49], v[152:155], v[190:193], v[46:49]
	v_mfma_f32_16x16x32_f16 v[42:45], v[174:177], v[190:193], v[42:45]
	v_mfma_f32_16x16x32_f16 v[30:33], v[152:155], v[198:201], v[30:33]
	v_mfma_f32_16x16x32_f16 v[26:29], v[174:177], v[198:201], v[26:29]
	v_mfma_f32_16x16x32_f16 v[14:17], v[152:155], v[206:209], v[14:17]
	v_mfma_f32_16x16x32_f16 v[10:13], v[174:177], v[206:209], v[10:13]
	s_barrier
	s_add_u32 s22, s34, 0x80000
	s_addc_u32 s23, s35, 0
	s_add_i32 s59, s61, s19
	s_mov_b32 m0, s59
	s_nop 0
	global_load_lds_dwordx4 v134, s[22:23]
	s_add_i32 m0, s59, 0x2000
	s_nop 0
	global_load_lds_dwordx4 v130, s[22:23]
	s_waitcnt vmcnt(6)
	s_barrier
; #define PG8_STAGE(bufoff, gbase, voff) do { _Pragma("unroll") for (int _i = 0; _i < 2; ++_i) \
;         __builtin_amdgcn_global_load_lds((const unsigned*)((const char*)(gbase) + (voff)[_i]), (LAS unsigned*)(lds + (bufoff) + ldsw + _i * 8192), 16, 0, 0); } while (0)
; #define PG8_LDA(dst, b, h) do { _Pragma("unroll") for (int m = 0; m < 4; ++m) _Pragma("unroll") for (int k = 0; k < 2; ++k) dst[m][k] = *(const LAS f16x8*)(lds + PG8_SA(b, h) + aoff + m * 2048 + k * 1024); } while (0)
; #define PG8_LDB(dst, b, h) do { _Pragma("unroll") for (int n = 0; n < 2; ++n) _Pragma("unroll") for (int k = 0; k < 2; ++k) dst[n][k] = *(const LAS f16x8*)(lds + PG8_SB(b, h) + boff + n * 2048 + k * 1024); } while (0)
; #define PG8_MMA(ai, bj, At, Bt) do { __builtin_amdgcn_s_setprio(1); _Pragma("unroll") for (int m = 0; m < 4; ++m) _Pragma("unroll") for (int n = 0; n < 2; ++n) _Pragma("unroll") for (int k = 0; k < 2; ++k) \
;         acc[ai][bj][m][n] = __builtin_amdgcn_mfma_f32_16x16x32_f16(Bt[n][k], At[m][k], acc[ai][bj][m][n], 0, 0, 0); __builtin_amdgcn_s_setprio(0); } while (0)
; #define PG8_WAIT_V(n) asm volatile("s_waitcnt vmcnt(" #n ")" ::: "memory")
; #define PG8_WAIT_L(n) asm volatile("s_waitcnt lgkmcnt(" #n ")" ::: "memory")
; #define PG8_BAR __builtin_amdgcn_s_barrier()
; #define PG8_SCHED __builtin_amdgcn_sched_barrier(0)
; template <class Epi>
; __device__ __forceinline__ void gemm_phase(LAS unsigned char* lds, const Gemm g0, const StaticOrder& S, const Epi& E) {
;     ...
;             PG8_WAIT_V(6); PG8_BAR; PG8_MMA(1, 1, At, B1); PG8_BAR;
;             PG8_LDB(B0, 1, 0); PG8_SCHED; PG8_LDA(At, 1, 0); PG8_STAGE(PG8_SA(0, 1), a2 + hstep, voffA);
;             PG8_WAIT_L(8); PG8_BAR; PG8_WAIT_L(0); PG8_MMA(0, 0, At, B0); PG8_BAR; PG8_SCHED;
;             PG8_LDB(B1, 1, 1); PG8_STAGE(PG8_SB(1, 0), b3, voffB);
;             PG8_BAR; PG8_WAIT_L(0); PG8_MMA(0, 1, At, B1); PG8_BAR;
;             PG8_LDA(At, 1, 1); PG8_STAGE(PG8_SA(1, 0), a3, voffA);
	v_mfma_f32_16x16x32_f16 v[54:57], v[210:213], v[178:181], v[54:57]
	v_mfma_f32_16x16x32_f16 v[50:53], v[238:241], v[178:181], v[50:53]
	v_mfma_f32_16x16x32_f16 v[38:41], v[210:213], v[186:189], v[38:41]
	v_mfma_f32_16x16x32_f16 v[34:37], v[238:241], v[186:189], v[34:37]
	v_mfma_f32_16x16x32_f16 v[22:25], v[210:213], v[194:197], v[22:25]
	v_mfma_f32_16x16x32_f16 v[18:21], v[238:241], v[194:197], v[18:21]
	v_mfma_f32_16x16x32_f16 v[6:9], v[210:213], v[202:205], v[6:9]
	v_mfma_f32_16x16x32_f16 v[2:5], v[238:241], v[202:205], v[2:5]
	v_mfma_f32_16x16x32_f16 v[54:57], v[234:237], v[182:185], v[54:57]
	v_mfma_f32_16x16x32_f16 v[50:53], v[242:245], v[182:185], v[50:53]
	v_mfma_f32_16x16x32_f16 v[38:41], v[234:237], v[190:193], v[38:41]
	v_mfma_f32_16x16x32_f16 v[34:37], v[242:245], v[190:193], v[34:37]
	v_mfma_f32_16x16x32_f16 v[22:25], v[234:237], v[198:201], v[22:25]
	v_mfma_f32_16x16x32_f16 v[18:21], v[242:245], v[198:201], v[18:21]
	v_mfma_f32_16x16x32_f16 v[6:9], v[234:237], v[206:209], v[6:9]
	v_mfma_f32_16x16x32_f16 v[2:5], v[242:245], v[206:209], v[2:5]
	s_add_i32 s59, 0, 0x18000
	v_add_u32_e32 v151, s59, v148
	s_barrier
	ds_read_b128 v[142:145], v151
	ds_read_b128 v[152:155], v151 offset:1024
	ds_read_b128 v[156:159], v151 offset:2048
	ds_read_b128 v[174:177], v151 offset:3072
	s_add_u32 s22, s36, 0x80000
	s_addc_u32 s23, s37, 0
	s_mov_b32 m0, s31
	ds_read_b128 v[178:181], v150 offset:32768
	ds_read_b128 v[182:185], v150 offset:33792
	ds_read_b128 v[186:189], v150 offset:34816
	ds_read_b128 v[190:193], v150 offset:35840
	ds_read_b128 v[194:197], v150 offset:36864
	ds_read_b128 v[198:201], v150 offset:37888
	ds_read_b128 v[202:205], v150 offset:38912
	ds_read_b128 v[206:209], v150 offset:39936
	global_load_lds_dwordx4 v136, s[22:23]
	v_lshl_add_u64 v[170:171], s[22:23], 0, v[132:133]
	s_mov_b32 m0, s38
	s_nop 0
	global_load_lds_dwordx4 v[170:171], off
	s_waitcnt lgkmcnt(8)
	s_barrier
	s_waitcnt lgkmcnt(0)
	s_waitcnt lgkmcnt(0)
	v_mfma_f32_16x16x32_f16 v[126:129], v[142:145], v[178:181], v[126:129]
	v_mfma_f32_16x16x32_f16 v[122:125], v[156:159], v[178:181], v[122:125]
	v_mfma_f32_16x16x32_f16 v[110:113], v[142:145], v[186:189], v[110:113]
	v_mfma_f32_16x16x32_f16 v[106:109], v[156:159], v[186:189], v[106:109]
	v_mfma_f32_16x16x32_f16 v[94:97], v[142:145], v[194:197], v[94:97]
	v_mfma_f32_16x16x32_f16 v[90:93], v[156:159], v[194:197], v[90:93]
	v_mfma_f32_16x16x32_f16 v[78:81], v[142:145], v[202:205], v[78:81]
	v_mfma_f32_16x16x32_f16 v[74:77], v[156:159], v[202:205], v[74:77]
	v_mfma_f32_16x16x32_f16 v[126:129], v[152:155], v[182:185], v[126:129]
	v_mfma_f32_16x16x32_f16 v[122:125], v[174:177], v[182:185], v[122:125]
	v_mfma_f32_16x16x32_f16 v[110:113], v[152:155], v[190:193], v[110:113]
	v_mfma_f32_16x16x32_f16 v[106:109], v[174:177], v[190:193], v[106:109]
	v_mfma_f32_16x16x32_f16 v[94:97], v[152:155], v[198:201], v[94:97]
	v_mfma_f32_16x16x32_f16 v[90:93], v[174:177], v[198:201], v[90:93]
	v_mfma_f32_16x16x32_f16 v[78:81], v[152:155], v[206:209], v[78:81]
	v_mfma_f32_16x16x32_f16 v[74:77], v[174:177], v[206:209], v[74:77]
	s_barrier
	s_add_i32 s36, 0, 0x1c000
	s_add_i32 s22, s59, s19
	v_add_u32_e32 v151, s36, v148
	v_lshl_add_u64 v[146:147], v[146:147], 0, s[64:65]
	s_mov_b32 m0, s22
	ds_read_b128 v[210:213], v151
	ds_read_b128 v[234:237], v151 offset:1024
	ds_read_b128 v[238:241], v151 offset:2048
	ds_read_b128 v[242:245], v151 offset:3072
	global_load_lds_dwordx4 v[146:147], off
	v_lshl_add_u64 v[146:147], v[160:161], 0, s[64:65]
	s_add_i32 m0, s22, 0x2000
	s_nop 0
	global_load_lds_dwordx4 v[146:147], off
	s_barrier
	s_waitcnt lgkmcnt(0)
	s_waitcnt lgkmcnt(0)
	v_mfma_f32_16x16x32_f16 v[118:121], v[210:213], v[178:181], v[118:121]
	v_mfma_f32_16x16x32_f16 v[114:117], v[238:241], v[178:181], v[114:117]
	v_mfma_f32_16x16x32_f16 v[102:105], v[210:213], v[186:189], v[102:105]
	v_mfma_f32_16x16x32_f16 v[98:101], v[238:241], v[186:189], v[98:101]
	v_mfma_f32_16x16x32_f16 v[86:89], v[210:213], v[194:197], v[86:89]
	v_mfma_f32_16x16x32_f16 v[82:85], v[238:241], v[194:197], v[82:85]
	v_mfma_f32_16x16x32_f16 v[70:73], v[210:213], v[202:205], v[70:73]
	v_mfma_f32_16x16x32_f16 v[66:69], v[238:241], v[202:205], v[66:69]
	v_mfma_f32_16x16x32_f16 v[118:121], v[234:237], v[182:185], v[118:121]
	v_mfma_f32_16x16x32_f16 v[114:117], v[242:245], v[182:185], v[114:117]
	v_mfma_f32_16x16x32_f16 v[102:105], v[234:237], v[190:193], v[102:105]
	v_mfma_f32_16x16x32_f16 v[98:101], v[242:245], v[190:193], v[98:101]
	v_mfma_f32_16x16x32_f16 v[86:89], v[234:237], v[198:201], v[86:89]
	v_mfma_f32_16x16x32_f16 v[82:85], v[242:245], v[198:201], v[82:85]
	v_mfma_f32_16x16x32_f16 v[70:73], v[234:237], v[206:209], v[70:73]
	v_mfma_f32_16x16x32_f16 v[66:69], v[242:245], v[206:209], v[66:69]
	s_mov_b32 m0, s39
	v_lshl_add_u64 v[146:147], v[162:163], 0, s[64:65]
	s_barrier
	ds_read_b128 v[178:181], v150 offset:49152
	ds_read_b128 v[182:185], v150 offset:50176
	ds_read_b128 v[186:189], v150 offset:51200
	ds_read_b128 v[190:193], v150 offset:52224
	ds_read_b128 v[194:197], v150 offset:53248
	ds_read_b128 v[198:201], v150 offset:54272
	ds_read_b128 v[202:205], v150 offset:55296
	ds_read_b128 v[206:209], v150 offset:56320
	global_load_lds_dwordx4 v[146:147], off
	v_lshl_add_u64 v[146:147], v[164:165], 0, s[64:65]
	s_mov_b32 m0, s48
	s_nop 0
	global_load_lds_dwordx4 v[146:147], off
	s_barrier
; __device__ __forceinline__ float gelu_tanh(float x) { const float y = 1.5957691216057308f * (x + 0.044715f * x * x * x); return x * fast_rcp(1.0f + __expf(-y)); }
; #define PG8_STAGE(bufoff, gbase, voff) do { _Pragma("unroll") for (int _i = 0; _i < 2; ++_i) \
;         __builtin_amdgcn_global_load_lds((const unsigned*)((const char*)(gbase) + (voff)[_i]), (LAS unsigned*)(lds + (bufoff) + ldsw + _i * 8192), 16, 0, 0); } while (0)
; #define PG8_MMA(ai, bj, At, Bt) do { __builtin_amdgcn_s_setprio(1); _Pragma("unroll") for (int m = 0; m < 4; ++m) _Pragma("unroll") for (int n = 0; n < 2; ++n) _Pragma("unroll") for (int k = 0; k < 2; ++k) \
;         acc[ai][bj][m][n] = __builtin_amdgcn_mfma_f32_16x16x32_f16(Bt[n][k], At[m][k], acc[ai][bj][m][n], 0, 0, 0); __builtin_amdgcn_s_setprio(0); } while (0)
; #define PG8_WAIT_V(n) asm volatile("s_waitcnt vmcnt(" #n ")" ::: "memory")
; #define PG8_WAIT_L(n) asm volatile("s_waitcnt lgkmcnt(" #n ")" ::: "memory")
; #define PG8_BAR __builtin_amdgcn_s_barrier()
; #define PG8_SCHED __builtin_amdgcn_sched_barrier(0)
;     __device__ __forceinline__ void operator()(f32x4 (&acc)[2][2][4][2], const Unit& u, int wr, int wc, int fr, int fq) const {
;     ...
;                 for (int bj = 0; bj < 2; ++bj) { f32x4 v0 = acc[ai][bj][m][0], v1 = acc[ai][bj][m][1];
;                     if (isy) {
; #pragma unroll
;                         for (int j = 0; j < 4; ++j) { v0[j] = gelu_tanh(v0[j]); v1[j] = gelu_tanh(v1[j]); } }
; template <class Epi>
; __device__ __forceinline__ void gemm_phase(LAS unsigned char* lds, const Gemm g0, const StaticOrder& S, const Epi& E) {
;     ...
;             PG8_BAR; PG8_WAIT_L(0); PG8_MMA(1, 0, At, B0); PG8_BAR; PG8_SCHED;
;             PG8_STAGE(PG8_SB(1, 1), b3 + hstep, voffB);
;             PG8_WAIT_V(6); PG8_BAR; PG8_MMA(1, 1, At, B1); PG8_BAR;
;         }
	s_waitcnt lgkmcnt(0)
	s_waitcnt lgkmcnt(0)
	v_mfma_f32_16x16x32_f16 v[62:65], v[142:145], v[178:181], v[62:65]
	v_mfma_f32_16x16x32_f16 v[58:61], v[156:159], v[178:181], v[58:61]
	v_mfma_f32_16x16x32_f16 v[46:49], v[142:145], v[186:189], v[46:49]
	v_mfma_f32_16x16x32_f16 v[42:45], v[156:159], v[186:189], v[42:45]
	v_mfma_f32_16x16x32_f16 v[30:33], v[142:145], v[194:197], v[30:33]
	v_mfma_f32_16x16x32_f16 v[26:29], v[156:159], v[194:197], v[26:29]
	v_mfma_f32_16x16x32_f16 v[14:17], v[142:145], v[202:205], v[14:17]
	v_mfma_f32_16x16x32_f16 v[10:13], v[156:159], v[202:205], v[10:13]
	v_mfma_f32_16x16x32_f16 v[62:65], v[152:155], v[182:185], v[62:65]
	v_mfma_f32_16x16x32_f16 v[58:61], v[174:177], v[182:185], v[58:61]
	v_mfma_f32_16x16x32_f16 v[46:49], v[152:155], v[190:193], v[46:49]
	v_mfma_f32_16x16x32_f16 v[42:45], v[174:177], v[190:193], v[42:45]
	v_mfma_f32_16x16x32_f16 v[30:33], v[152:155], v[198:201], v[30:33]
	v_mfma_f32_16x16x32_f16 v[26:29], v[174:177], v[198:201], v[26:29]
	v_mfma_f32_16x16x32_f16 v[14:17], v[152:155], v[206:209], v[14:17]
	v_mfma_f32_16x16x32_f16 v[10:13], v[174:177], v[206:209], v[10:13]
	s_barrier
	s_add_u32 s22, s34, 0x80080
	s_addc_u32 s23, s35, 0
	s_add_i32 s34, s36, s19
	s_mov_b32 m0, s34
	s_nop 0
	global_load_lds_dwordx4 v134, s[22:23]
	s_add_i32 m0, s34, 0x2000
	s_nop 0
	global_load_lds_dwordx4 v130, s[22:23]
	s_waitcnt vmcnt(6)
	s_barrier
	v_mfma_f32_16x16x32_f16 v[54:57], v[210:213], v[178:181], v[54:57]
	v_mfma_f32_16x16x32_f16 v[50:53], v[238:241], v[178:181], v[50:53]
	v_mfma_f32_16x16x32_f16 v[38:41], v[210:213], v[186:189], v[38:41]
	v_mfma_f32_16x16x32_f16 v[34:37], v[238:241], v[186:189], v[34:37]
	v_mfma_f32_16x16x32_f16 v[22:25], v[210:213], v[194:197], v[22:25]
	v_mfma_f32_16x16x32_f16 v[18:21], v[238:241], v[194:197], v[18:21]
	v_mfma_f32_16x16x32_f16 v[6:9], v[210:213], v[202:205], v[6:9]
	v_mfma_f32_16x16x32_f16 v[2:5], v[238:241], v[202:205], v[2:5]
	v_mfma_f32_16x16x32_f16 v[54:57], v[234:237], v[182:185], v[54:57]
	v_mfma_f32_16x16x32_f16 v[50:53], v[242:245], v[182:185], v[50:53]
	v_mfma_f32_16x16x32_f16 v[38:41], v[234:237], v[190:193], v[38:41]
	v_mfma_f32_16x16x32_f16 v[34:37], v[242:245], v[190:193], v[34:37]
	v_mfma_f32_16x16x32_f16 v[22:25], v[234:237], v[198:201], v[22:25]
	v_mfma_f32_16x16x32_f16 v[18:21], v[242:245], v[198:201], v[18:21]
	v_mfma_f32_16x16x32_f16 v[6:9], v[234:237], v[206:209], v[6:9]
	v_mfma_f32_16x16x32_f16 v[2:5], v[242:245], v[206:209], v[2:5]
	s_add_i32 s58, s58, 2
	s_add_u32 s25, s25, 0x100
	s_addc_u32 s53, s53, 0
	s_add_u32 s6, s6, 0x100
	s_addc_u32 s7, s7, 0
	s_cmp_gt_u32 s58, 29
	s_barrier
	s_cbranch_scc0 .LBB0_302
	s_cmp_lt_i32 s51, 8
	s_cselect_b64 s[34:35], -1, 0
	s_cmp_gt_i32 s51, 7
	s_cbranch_scc1 .LBB0_305
	v_mul_f32_e32 v143, 0x3d372713, v122
	v_mul_f32_e32 v143, v122, v143
	v_fma_f32 v143, v122, v143, v122
	v_mul_f32_e32 v143, 0xbfcc422a, v143
	v_mul_f32_e32 v143, 0x3fb8aa3b, v143
	v_exp_f32_e32 v143, v143
	v_mul_f32_e32 v142, 0x3d372713, v126
	v_mul_f32_e32 v142, v126, v142
	v_fma_f32 v142, v126, v142, v126
	v_add_f32_e32 v143, 1.0, v143
	v_rcp_f32_e32 v144, v143
	v_mul_f32_e32 v143, 0x3d372713, v127
	v_mul_f32_e32 v143, v127, v143
	v_fma_f32 v143, v127, v143, v127
	v_mul_f32_e32 v142, 0xbfcc422a, v142
	v_mul_f32_e32 v143, 0xbfcc422a, v143
	v_mul_f32_e32 v142, 0x3fb8aa3b, v142
	v_mul_f32_e32 v143, 0x3fb8aa3b, v143
	v_mul_f32_e32 v147, 0x3d372713, v124
	v_exp_f32_e32 v142, v142
	v_exp_f32_e32 v143, v143
	v_mul_f32_e32 v147, v124, v147
	v_fma_f32 v147, v124, v147, v124
	v_mul_f32_e32 v147, 0xbfcc422a, v147
	v_mul_f32_e32 v147, 0x3fb8aa3b, v147
	v_add_f32_e32 v142, 1.0, v142
	v_add_f32_e32 v143, 1.0, v143
	v_exp_f32_e32 v147, v147
	v_rcp_f32_e32 v142, v142
	v_rcp_f32_e32 v143, v143
	v_mul_f32_e32 v145, 0x3d372713, v123
	v_add_f32_e32 v147, 1.0, v147
	v_mul_f32_e32 v146, 0x3d372713, v128
	v_rcp_f32_e32 v152, v147
	v_mul_f32_e32 v147, 0x3d372713, v129
	v_pk_mul_f32 v[126:127], v[126:127], v[142:143]
	v_mul_f32_e32 v142, 0x3d372713, v125
	v_mul_f32_e32 v145, v123, v145
	v_mul_f32_e32 v146, v128, v146
	v_mul_f32_e32 v147, v129, v147
	v_mul_f32_e32 v142, v125, v142
	v_fma_f32 v145, v123, v145, v123
	v_fma_f32 v146, v128, v146, v128
	v_fma_f32 v147, v129, v147, v129
	v_fma_f32 v142, v125, v142, v125
	v_mul_f32_e32 v145, 0xbfcc422a, v145
	v_mul_f32_e32 v146, 0xbfcc422a, v146
	v_mul_f32_e32 v147, 0xbfcc422a, v147
	v_mul_f32_e32 v142, 0xbfcc422a, v142
	v_mul_f32_e32 v145, 0x3fb8aa3b, v145
	v_mul_f32_e32 v146, 0x3fb8aa3b, v146
	v_mul_f32_e32 v147, 0x3fb8aa3b, v147
	v_mul_f32_e32 v142, 0x3fb8aa3b, v142
	v_exp_f32_e32 v145, v145
	v_exp_f32_e32 v146, v146
	v_exp_f32_e32 v147, v147
	v_exp_f32_e32 v142, v142
	v_add_f32_e32 v145, 1.0, v145
	v_add_f32_e32 v146, 1.0, v146
	v_add_f32_e32 v147, 1.0, v147
	v_add_f32_e32 v142, 1.0, v142
	v_rcp_f32_e32 v145, v145
	v_rcp_f32_e32 v146, v146
	v_rcp_f32_e32 v147, v147
	v_rcp_f32_e32 v153, v142
	v_pk_mul_f32 v[122:123], v[122:123], v[144:145]
	v_pk_mul_f32 v[128:129], v[128:129], v[146:147]
	v_pk_mul_f32 v[124:125], v[124:125], v[152:153]

;     __device__ __forceinline__ void prefetch(const Unit& u, int wr, int wc, int lane) const { lnfold_prefetch(vl, stats, gW, bW, u, wr, wc, lane); }
;     __device__ __forceinline__ void prefetch(const Unit& u, int wr, int wc, int lane) const { lnfold_prefetch(vl, stats, gW, bW, u, wr, wc, lane); }
; #define PG8_STAGE(bufoff, gbase, voff) do { _Pragma("unroll") for (int _i = 0; _i < 2; ++_i) \
;         __builtin_amdgcn_global_load_lds((const unsigned*)((const char*)(gbase) + (voff)[_i]), (LAS unsigned*)(lds + (bufoff) + ldsw + _i * 8192), 16, 0, 0); } while (0)
; #define PG8_LDA(dst, b, h) do { _Pragma("unroll") for (int m = 0; m < 4; ++m) _Pragma("unroll") for (int k = 0; k < 2; ++k) dst[m][k] = *(const LAS f16x8*)(lds + PG8_SA(b, h) + aoff + m * 2048 + k * 1024); } while (0)
; #define PG8_LDB(dst, b, h) do { _Pragma("unroll") for (int n = 0; n < 2; ++n) _Pragma("unroll") for (int k = 0; k < 2; ++k) dst[n][k] = *(const LAS f16x8*)(lds + PG8_SB(b, h) + boff + n * 2048 + k * 1024); } while (0)
; #define PG8_MMA(ai, bj, At, Bt) do { __builtin_amdgcn_s_setprio(1); _Pragma("unroll") for (int m = 0; m < 4; ++m) _Pragma("unroll") for (int n = 0; n < 2; ++n) _Pragma("unroll") for (int k = 0; k < 2; ++k) \
;         acc[ai][bj][m][n] = __builtin_amdgcn_mfma_f32_16x16x32_f16(Bt[n][k], At[m][k], acc[ai][bj][m][n], 0, 0, 0); __builtin_amdgcn_s_setprio(0); } while (0)
; template <class Epi>
; __device__ __forceinline__ void gemm_phase(LAS unsigned char* lds, const Gemm g0, const StaticOrder& S, const Epi& E) {
;     ...
;             const bool last = (t == nt - 2);
;             if (Epi::PREF && last) E.prefetch(cur, wr, wc, lane);
;             const char* a1 = cA + (size_t)(t + 1) * kstep;
;             const char* a2 = last ? nA : cA + (size_t)(t + 2) * kstep; const char* b2 = last ? nB : cB + (size_t)(t + 2) * kstep;
;             const char* a3 = a2 + kstep; const char* b3 = b2 + kstep;
;             PG8_LDB(B0, 0, 0); PG8_SCHED; PG8_LDA(At, 0, 0); PG8_STAGE(PG8_SA(1, 1), a1 + hstep, voffA);
;             PG8_WAIT_L(8); PG8_BAR; PG8_WAIT_L(0); PG8_MMA(0, 0, At, B0); PG8_BAR; PG8_SCHED;
;             PG8_LDB(B1, 0, 1); PG8_STAGE(PG8_SB(0, 0), b2, voffB);
;             PG8_BAR; PG8_WAIT_L(0); PG8_MMA(0, 1, At, B1); PG8_BAR;
;             PG8_LDA(At, 0, 1); PG8_STAGE(PG8_SA(0, 0), a2, voffA);
;             PG8_BAR; PG8_WAIT_L(0); PG8_MMA(1, 0, At, B0); PG8_BAR; PG8_SCHED;
.LBB0_512:
	s_add_u32 s23, s12, 0xfff80080
	s_addc_u32 s48, s13, -1
	s_add_i32 s90, 0, 0x10000
	v_add_u32_e32 v142, s90, v205
	ds_read_b128 v[122:125], v142
	ds_read_b128 v[126:129], v142 offset:1024
	ds_read_b128 v[138:141], v142 offset:2048
	ds_read_b128 v[142:145], v142 offset:3072
	s_cmp_eq_u32 s22, 28
	s_cselect_b32 s51, s15, s48
	s_cselect_b32 s50, s24, s23
	s_cselect_b32 s49, s25, vcc_hi
	s_cselect_b32 s48, s53, vcc_lo
	s_add_i32 m0, s71, 0xc000
	ds_read_b128 v[146:149], v210
	ds_read_b128 v[150:153], v210 offset:1024
	ds_read_b128 v[154:157], v210 offset:2048
	ds_read_b128 v[158:161], v210 offset:3072
	ds_read_b128 v[188:191], v210 offset:4096
	ds_read_b128 v[192:195], v210 offset:5120
	ds_read_b128 v[196:199], v210 offset:6144
	ds_read_b128 v[200:203], v210 offset:7168
	global_load_lds_dwordx4 v186, s[12:13]
	s_add_i32 m0, s71, 0xe000
	s_nop 0
	global_load_lds_dwordx4 v184, s[12:13]
	s_waitcnt lgkmcnt(8)
	s_barrier
	s_waitcnt lgkmcnt(0)
	s_waitcnt lgkmcnt(0)
	v_mfma_f32_16x16x32_f16 v[134:137], v[122:125], v[146:149], v[134:137]
	v_mfma_f32_16x16x32_f16 v[130:133], v[138:141], v[146:149], v[130:133]
	v_mfma_f32_16x16x32_f16 v[110:113], v[122:125], v[154:157], v[110:113]
	v_mfma_f32_16x16x32_f16 v[106:109], v[138:141], v[154:157], v[106:109]
	v_mfma_f32_16x16x32_f16 v[94:97], v[122:125], v[188:191], v[94:97]
	v_mfma_f32_16x16x32_f16 v[90:93], v[138:141], v[188:191], v[90:93]
	v_mfma_f32_16x16x32_f16 v[78:81], v[122:125], v[196:199], v[78:81]
	v_mfma_f32_16x16x32_f16 v[74:77], v[138:141], v[196:199], v[74:77]
	v_mfma_f32_16x16x32_f16 v[134:137], v[126:129], v[150:153], v[134:137]
	v_mfma_f32_16x16x32_f16 v[130:133], v[142:145], v[150:153], v[130:133]
	v_mfma_f32_16x16x32_f16 v[110:113], v[126:129], v[158:161], v[110:113]
	v_mfma_f32_16x16x32_f16 v[106:109], v[142:145], v[158:161], v[106:109]
	v_mfma_f32_16x16x32_f16 v[94:97], v[126:129], v[192:195], v[94:97]
	v_mfma_f32_16x16x32_f16 v[90:93], v[142:145], v[192:195], v[90:93]
	v_mfma_f32_16x16x32_f16 v[78:81], v[126:129], v[200:203], v[78:81]
	v_mfma_f32_16x16x32_f16 v[74:77], v[142:145], v[200:203], v[74:77]
	s_barrier
	s_add_i32 s23, 0, 0x14000
	v_add_u32_e32 v162, s23, v205
	s_add_i32 s90, s90, s75
	ds_read_b128 v[212:215], v162
	ds_read_b128 v[234:237], v162 offset:1024
	ds_read_b128 v[238:241], v162 offset:2048
	ds_read_b128 v[242:245], v162 offset:3072
	v_lshl_add_u64 v[162:163], s[48:49], 0, v[178:179]
	s_mov_b32 m0, s90
	v_lshl_add_u64 v[164:165], s[48:49], 0, v[174:175]
	global_load_lds_dwordx4 v[162:163], off
	s_add_i32 m0, s90, 0x2000
	s_nop 0
	global_load_lds_dwordx4 v[164:165], off
	s_barrier
	s_waitcnt lgkmcnt(0)
	s_waitcnt lgkmcnt(0)
	v_mfma_f32_16x16x32_f16 v[118:121], v[212:215], v[146:149], v[118:121]
	v_mfma_f32_16x16x32_f16 v[114:117], v[238:241], v[146:149], v[114:117]
	v_mfma_f32_16x16x32_f16 v[102:105], v[212:215], v[154:157], v[102:105]
	v_mfma_f32_16x16x32_f16 v[98:101], v[238:241], v[154:157], v[98:101]
	v_mfma_f32_16x16x32_f16 v[86:89], v[212:215], v[188:191], v[86:89]
	v_mfma_f32_16x16x32_f16 v[82:85], v[238:241], v[188:191], v[82:85]
	v_mfma_f32_16x16x32_f16 v[70:73], v[212:215], v[196:199], v[70:73]
	v_mfma_f32_16x16x32_f16 v[66:69], v[238:241], v[196:199], v[66:69]
	v_mfma_f32_16x16x32_f16 v[118:121], v[234:237], v[150:153], v[118:121]
	v_mfma_f32_16x16x32_f16 v[114:117], v[242:245], v[150:153], v[114:117]
	v_mfma_f32_16x16x32_f16 v[102:105], v[234:237], v[158:161], v[102:105]
	v_mfma_f32_16x16x32_f16 v[98:101], v[242:245], v[158:161], v[98:101]
	v_mfma_f32_16x16x32_f16 v[86:89], v[234:237], v[192:195], v[86:89]
	v_mfma_f32_16x16x32_f16 v[82:85], v[242:245], v[192:195], v[82:85]
	v_mfma_f32_16x16x32_f16 v[70:73], v[234:237], v[200:203], v[70:73]
	v_mfma_f32_16x16x32_f16 v[66:69], v[242:245], v[200:203], v[66:69]
	s_mov_b32 m0, s71
	v_lshl_add_u64 v[170:171], s[50:51], 0, v[180:181]
	s_barrier
	ds_read_b128 v[146:149], v210 offset:16384
	ds_read_b128 v[150:153], v210 offset:17408
	ds_read_b128 v[154:157], v210 offset:18432
	ds_read_b128 v[158:161], v210 offset:19456
	ds_read_b128 v[188:191], v210 offset:20480
	ds_read_b128 v[192:195], v210 offset:21504
	ds_read_b128 v[196:199], v210 offset:22528
	ds_read_b128 v[200:203], v210 offset:23552
	global_load_lds_dwordx4 v[170:171], off
	v_lshl_add_u64 v[172:173], s[50:51], 0, v[176:177]
	s_mov_b32 m0, s61
	s_nop 0
	global_load_lds_dwordx4 v[172:173], off
	s_barrier
	s_waitcnt lgkmcnt(0)
	s_waitcnt lgkmcnt(0)
	v_mfma_f32_16x16x32_f16 v[62:65], v[122:125], v[146:149], v[62:65]
	v_mfma_f32_16x16x32_f16 v[58:61], v[138:141], v[146:149], v[58:61]
	v_mfma_f32_16x16x32_f16 v[46:49], v[122:125], v[154:157], v[46:49]
	v_mfma_f32_16x16x32_f16 v[42:45], v[138:141], v[154:157], v[42:45]
	v_mfma_f32_16x16x32_f16 v[30:33], v[122:125], v[188:191], v[30:33]
	v_mfma_f32_16x16x32_f16 v[26:29], v[138:141], v[188:191], v[26:29]
	v_mfma_f32_16x16x32_f16 v[14:17], v[122:125], v[196:199], v[14:17]
	v_mfma_f32_16x16x32_f16 v[10:13], v[138:141], v[196:199], v[10:13]
	v_mfma_f32_16x16x32_f16 v[62:65], v[126:129], v[150:153], v[62:65]
	v_mfma_f32_16x16x32_f16 v[58:61], v[142:145], v[150:153], v[58:61]
	v_mfma_f32_16x16x32_f16 v[46:49], v[126:129], v[158:161], v[46:49]
	v_mfma_f32_16x16x32_f16 v[42:45], v[142:145], v[158:161], v[42:45]
	v_mfma_f32_16x16x32_f16 v[30:33], v[126:129], v[192:195], v[30:33]
	v_mfma_f32_16x16x32_f16 v[26:29], v[142:145], v[192:195], v[26:29]
	v_mfma_f32_16x16x32_f16 v[14:17], v[126:129], v[200:203], v[14:17]
	v_mfma_f32_16x16x32_f16 v[10:13], v[142:145], v[200:203], v[10:13]
	s_barrier
; #define PG8_STAGE(bufoff, gbase, voff) do { _Pragma("unroll") for (int _i = 0; _i < 2; ++_i) \
;         __builtin_amdgcn_global_load_lds((const unsigned*)((const char*)(gbase) + (voff)[_i]), (LAS unsigned*)(lds + (bufoff) + ldsw + _i * 8192), 16, 0, 0); } while (0)
; #define PG8_LDA(dst, b, h) do { _Pragma("unroll") for (int m = 0; m < 4; ++m) _Pragma("unroll") for (int k = 0; k < 2; ++k) dst[m][k] = *(const LAS f16x8*)(lds + PG8_SA(b, h) + aoff + m * 2048 + k * 1024); } while (0)
; #define PG8_LDB(dst, b, h) do { _Pragma("unroll") for (int n = 0; n < 2; ++n) _Pragma("unroll") for (int k = 0; k < 2; ++k) dst[n][k] = *(const LAS f16x8*)(lds + PG8_SB(b, h) + boff + n * 2048 + k * 1024); } while (0)
; #define PG8_MMA(ai, bj, At, Bt) do { __builtin_amdgcn_s_setprio(1); _Pragma("unroll") for (int m = 0; m < 4; ++m) _Pragma("unroll") for (int n = 0; n < 2; ++n) _Pragma("unroll") for (int k = 0; k < 2; ++k) \
;         acc[ai][bj][m][n] = __builtin_amdgcn_mfma_f32_16x16x32_f16(Bt[n][k], At[m][k], acc[ai][bj][m][n], 0, 0, 0); __builtin_amdgcn_s_setprio(0); } while (0)
; #define PG8_WAIT_V(n) asm volatile("s_waitcnt vmcnt(" #n ")" ::: "memory")
; #define PG8_WAIT_L(n) asm volatile("s_waitcnt lgkmcnt(" #n ")" ::: "memory")
; #define PG8_BAR __builtin_amdgcn_s_barrier()
; #define PG8_SCHED __builtin_amdgcn_sched_barrier(0)
; template <class Epi>
; __device__ __forceinline__ void gemm_phase(LAS unsigned char* lds, const Gemm g0, const StaticOrder& S, const Epi& E) {
;     ...
;             PG8_STAGE(PG8_SB(0, 1), b2 + hstep, voffB);
;             PG8_WAIT_V(6); PG8_BAR; PG8_MMA(1, 1, At, B1); PG8_BAR;
;             PG8_LDB(B0, 1, 0); PG8_SCHED; PG8_LDA(At, 1, 0); PG8_STAGE(PG8_SA(0, 1), a2 + hstep, voffA);
;             PG8_WAIT_L(8); PG8_BAR; PG8_WAIT_L(0); PG8_MMA(0, 0, At, B0); PG8_BAR; PG8_SCHED;
;             PG8_LDB(B1, 1, 1); PG8_STAGE(PG8_SB(1, 0), b3, voffB);
;             PG8_BAR; PG8_WAIT_L(0); PG8_MMA(0, 1, At, B1); PG8_BAR;
	s_add_u32 s90, s48, 0x80000
	s_addc_u32 s91, s49, 0
	s_add_i32 s23, s23, s75
	s_mov_b32 m0, s23
	s_nop 0
	global_load_lds_dwordx4 v178, s[90:91]
	s_add_i32 m0, s23, 0x2000
	s_nop 0
	global_load_lds_dwordx4 v174, s[90:91]
	s_waitcnt vmcnt(6)
	s_barrier
	v_mfma_f32_16x16x32_f16 v[54:57], v[212:215], v[146:149], v[54:57]
	v_mfma_f32_16x16x32_f16 v[50:53], v[238:241], v[146:149], v[50:53]
	v_mfma_f32_16x16x32_f16 v[38:41], v[212:215], v[154:157], v[38:41]
	v_mfma_f32_16x16x32_f16 v[34:37], v[238:241], v[154:157], v[34:37]
	v_mfma_f32_16x16x32_f16 v[22:25], v[212:215], v[188:191], v[22:25]
	v_mfma_f32_16x16x32_f16 v[18:21], v[238:241], v[188:191], v[18:21]
	v_mfma_f32_16x16x32_f16 v[6:9], v[212:215], v[196:199], v[6:9]
	v_mfma_f32_16x16x32_f16 v[2:5], v[238:241], v[196:199], v[2:5]
	v_mfma_f32_16x16x32_f16 v[54:57], v[234:237], v[150:153], v[54:57]
	v_mfma_f32_16x16x32_f16 v[50:53], v[242:245], v[150:153], v[50:53]
	v_mfma_f32_16x16x32_f16 v[38:41], v[234:237], v[158:161], v[38:41]
	v_mfma_f32_16x16x32_f16 v[34:37], v[242:245], v[158:161], v[34:37]
	v_mfma_f32_16x16x32_f16 v[22:25], v[234:237], v[192:195], v[22:25]
	v_mfma_f32_16x16x32_f16 v[18:21], v[242:245], v[192:195], v[18:21]
	v_mfma_f32_16x16x32_f16 v[6:9], v[234:237], v[200:203], v[6:9]
	v_mfma_f32_16x16x32_f16 v[2:5], v[242:245], v[200:203], v[2:5]
	s_add_i32 s23, 0, 0x18000
	v_add_u32_e32 v142, s23, v205
	s_barrier
	ds_read_b128 v[122:125], v142
	ds_read_b128 v[126:129], v142 offset:1024
	ds_read_b128 v[138:141], v142 offset:2048
	ds_read_b128 v[142:145], v142 offset:3072
	s_add_u32 s50, s50, 0x80000
	s_addc_u32 s51, s51, 0
	s_mov_b32 m0, s74
	ds_read_b128 v[146:149], v210 offset:32768
	ds_read_b128 v[150:153], v210 offset:33792
	ds_read_b128 v[154:157], v210 offset:34816
	ds_read_b128 v[158:161], v210 offset:35840
	ds_read_b128 v[188:191], v210 offset:36864
	ds_read_b128 v[192:195], v210 offset:37888
	ds_read_b128 v[196:199], v210 offset:38912
	ds_read_b128 v[200:203], v210 offset:39936
	global_load_lds_dwordx4 v180, s[50:51]
	s_mov_b32 m0, s18
	s_nop 0
	global_load_lds_dwordx4 v176, s[50:51]
	s_waitcnt lgkmcnt(8)
	s_barrier
	s_waitcnt lgkmcnt(0)
	s_waitcnt lgkmcnt(0)
	v_mfma_f32_16x16x32_f16 v[134:137], v[122:125], v[146:149], v[134:137]
	v_mfma_f32_16x16x32_f16 v[130:133], v[138:141], v[146:149], v[130:133]
	v_mfma_f32_16x16x32_f16 v[110:113], v[122:125], v[154:157], v[110:113]
	v_mfma_f32_16x16x32_f16 v[106:109], v[138:141], v[154:157], v[106:109]
	v_mfma_f32_16x16x32_f16 v[94:97], v[122:125], v[188:191], v[94:97]
	v_mfma_f32_16x16x32_f16 v[90:93], v[138:141], v[188:191], v[90:93]
	v_mfma_f32_16x16x32_f16 v[78:81], v[122:125], v[196:199], v[78:81]
	v_mfma_f32_16x16x32_f16 v[74:77], v[138:141], v[196:199], v[74:77]
	v_mfma_f32_16x16x32_f16 v[134:137], v[126:129], v[150:153], v[134:137]
	v_mfma_f32_16x16x32_f16 v[130:133], v[142:145], v[150:153], v[130:133]
	v_mfma_f32_16x16x32_f16 v[110:113], v[126:129], v[158:161], v[110:113]
	v_mfma_f32_16x16x32_f16 v[106:109], v[142:145], v[158:161], v[106:109]
	v_mfma_f32_16x16x32_f16 v[94:97], v[126:129], v[192:195], v[94:97]
	v_mfma_f32_16x16x32_f16 v[90:93], v[142:145], v[192:195], v[90:93]
	v_mfma_f32_16x16x32_f16 v[78:81], v[126:129], v[200:203], v[78:81]
	v_mfma_f32_16x16x32_f16 v[74:77], v[142:145], v[200:203], v[74:77]
	s_barrier
	s_add_i32 s50, 0, 0x1c000
	s_add_i32 s23, s23, s75
	v_add_u32_e32 v211, s50, v205
	v_lshl_add_u64 v[162:163], v[162:163], 0, s[64:65]
	s_mov_b32 m0, s23
	ds_read_b128 v[212:215], v211
	ds_read_b128 v[234:237], v211 offset:1024
	ds_read_b128 v[238:241], v211 offset:2048
	ds_read_b128 v[242:245], v211 offset:3072
	global_load_lds_dwordx4 v[162:163], off
	v_lshl_add_u64 v[162:163], v[164:165], 0, s[64:65]
	s_add_i32 m0, s23, 0x2000
	s_nop 0
	global_load_lds_dwordx4 v[162:163], off
	s_barrier
; #define GAS __attribute__((address_space(1)))
; #define PG8_STAGE(bufoff, gbase, voff) do { _Pragma("unroll") for (int _i = 0; _i < 2; ++_i) \
;         __builtin_amdgcn_global_load_lds((const unsigned*)((const char*)(gbase) + (voff)[_i]), (LAS unsigned*)(lds + (bufoff) + ldsw + _i * 8192), 16, 0, 0); } while (0)
; #define PG8_LDA(dst, b, h) do { _Pragma("unroll") for (int m = 0; m < 4; ++m) _Pragma("unroll") for (int k = 0; k < 2; ++k) dst[m][k] = *(const LAS f16x8*)(lds + PG8_SA(b, h) + aoff + m * 2048 + k * 1024); } while (0)
; #define PG8_MMA(ai, bj, At, Bt) do { __builtin_amdgcn_s_setprio(1); _Pragma("unroll") for (int m = 0; m < 4; ++m) _Pragma("unroll") for (int n = 0; n < 2; ++n) _Pragma("unroll") for (int k = 0; k < 2; ++k) \
;         acc[ai][bj][m][n] = __builtin_amdgcn_mfma_f32_16x16x32_f16(Bt[n][k], At[m][k], acc[ai][bj][m][n], 0, 0, 0); __builtin_amdgcn_s_setprio(0); } while (0)
; #define PG8_WAIT_V(n) asm volatile("s_waitcnt vmcnt(" #n ")" ::: "memory")
; #define PG8_WAIT_L(n) asm volatile("s_waitcnt lgkmcnt(" #n ")" ::: "memory")
; #define PG8_BAR __builtin_amdgcn_s_barrier()
; #define PG8_SCHED __builtin_amdgcn_sched_barrier(0)
;     __device__ __forceinline__ void operator()(f32x4 (&acc)[2][2][4][2], const Unit& u, int wr, int wc, int fr, int fq) const {
;     ...
;         { const int lane = fr + 16 * fq, cL = u.pn * BM + wc * 32 + (lane < 32 ? lane : 96 + lane);
;           float vg = 0.f, vb = 0.f, vt = 0.f;
;           if (hasln) { vg = *(const GAS float*)(pg + cL); vb = *(const GAS float*)(pb + cL); }
; template <class Epi>
; __device__ __forceinline__ void gemm_phase(LAS unsigned char* lds, const Gemm g0, const StaticOrder& S, const Epi& E) {
;     ...
;             PG8_LDA(At, 1, 1); PG8_STAGE(PG8_SA(1, 0), a3, voffA);
;             PG8_BAR; PG8_WAIT_L(0); PG8_MMA(1, 0, At, B0); PG8_BAR; PG8_SCHED;
;             PG8_STAGE(PG8_SB(1, 1), b3 + hstep, voffB);
;             PG8_WAIT_V(6); PG8_BAR; PG8_MMA(1, 1, At, B1); PG8_BAR;
;         }
	s_waitcnt lgkmcnt(0)
	s_waitcnt lgkmcnt(0)
	v_mfma_f32_16x16x32_f16 v[118:121], v[212:215], v[146:149], v[118:121]
	v_mfma_f32_16x16x32_f16 v[114:117], v[238:241], v[146:149], v[114:117]
	v_mfma_f32_16x16x32_f16 v[102:105], v[212:215], v[154:157], v[102:105]
	v_mfma_f32_16x16x32_f16 v[98:101], v[238:241], v[154:157], v[98:101]
	v_mfma_f32_16x16x32_f16 v[86:89], v[212:215], v[188:191], v[86:89]
	v_mfma_f32_16x16x32_f16 v[82:85], v[238:241], v[188:191], v[82:85]
	v_mfma_f32_16x16x32_f16 v[70:73], v[212:215], v[196:199], v[70:73]
	v_mfma_f32_16x16x32_f16 v[66:69], v[238:241], v[196:199], v[66:69]
	v_mfma_f32_16x16x32_f16 v[118:121], v[234:237], v[150:153], v[118:121]
	v_mfma_f32_16x16x32_f16 v[114:117], v[242:245], v[150:153], v[114:117]
	v_mfma_f32_16x16x32_f16 v[102:105], v[234:237], v[158:161], v[102:105]
	v_mfma_f32_16x16x32_f16 v[98:101], v[242:245], v[158:161], v[98:101]
	v_mfma_f32_16x16x32_f16 v[86:89], v[234:237], v[192:195], v[86:89]
	v_mfma_f32_16x16x32_f16 v[82:85], v[242:245], v[192:195], v[82:85]
	v_mfma_f32_16x16x32_f16 v[70:73], v[234:237], v[200:203], v[70:73]
	v_mfma_f32_16x16x32_f16 v[66:69], v[242:245], v[200:203], v[66:69]
	s_mov_b32 m0, s28
	v_lshl_add_u64 v[162:163], v[170:171], 0, s[64:65]
	s_barrier
	ds_read_b128 v[146:149], v210 offset:49152
	ds_read_b128 v[150:153], v210 offset:50176
	ds_read_b128 v[154:157], v210 offset:51200
	ds_read_b128 v[158:161], v210 offset:52224
	ds_read_b128 v[188:191], v210 offset:53248
	ds_read_b128 v[192:195], v210 offset:54272
	ds_read_b128 v[196:199], v210 offset:55296
	ds_read_b128 v[200:203], v210 offset:56320
	global_load_lds_dwordx4 v[162:163], off
	v_lshl_add_u64 v[162:163], v[172:173], 0, s[64:65]
	s_mov_b32 m0, s29
	s_nop 0
	global_load_lds_dwordx4 v[162:163], off
	s_barrier
	s_waitcnt lgkmcnt(0)
	s_waitcnt lgkmcnt(0)
	v_mfma_f32_16x16x32_f16 v[62:65], v[122:125], v[146:149], v[62:65]
	v_mfma_f32_16x16x32_f16 v[58:61], v[138:141], v[146:149], v[58:61]
	v_mfma_f32_16x16x32_f16 v[46:49], v[122:125], v[154:157], v[46:49]
	v_mfma_f32_16x16x32_f16 v[42:45], v[138:141], v[154:157], v[42:45]
	v_mfma_f32_16x16x32_f16 v[30:33], v[122:125], v[188:191], v[30:33]
	v_mfma_f32_16x16x32_f16 v[26:29], v[138:141], v[188:191], v[26:29]
	v_mfma_f32_16x16x32_f16 v[14:17], v[122:125], v[196:199], v[14:17]
	v_mfma_f32_16x16x32_f16 v[10:13], v[138:141], v[196:199], v[10:13]
	v_mfma_f32_16x16x32_f16 v[62:65], v[126:129], v[150:153], v[62:65]
	v_mfma_f32_16x16x32_f16 v[58:61], v[142:145], v[150:153], v[58:61]
	v_mfma_f32_16x16x32_f16 v[46:49], v[126:129], v[158:161], v[46:49]
	v_mfma_f32_16x16x32_f16 v[42:45], v[142:145], v[158:161], v[42:45]
	v_mfma_f32_16x16x32_f16 v[30:33], v[126:129], v[192:195], v[30:33]
	v_mfma_f32_16x16x32_f16 v[26:29], v[142:145], v[192:195], v[26:29]
	v_mfma_f32_16x16x32_f16 v[14:17], v[126:129], v[200:203], v[14:17]
	v_mfma_f32_16x16x32_f16 v[10:13], v[142:145], v[200:203], v[10:13]
	s_barrier
	s_add_u32 s48, s48, 0x80080
	s_addc_u32 s49, s49, 0
	s_add_i32 s23, s50, s75
	s_mov_b32 m0, s23
	s_nop 0
	global_load_lds_dwordx4 v178, s[48:49]
	s_add_i32 m0, s23, 0x2000
	s_nop 0
	global_load_lds_dwordx4 v174, s[48:49]
	s_waitcnt vmcnt(6)
	s_barrier
	v_mfma_f32_16x16x32_f16 v[54:57], v[212:215], v[146:149], v[54:57]
	v_mfma_f32_16x16x32_f16 v[50:53], v[238:241], v[146:149], v[50:53]
	v_mfma_f32_16x16x32_f16 v[38:41], v[212:215], v[154:157], v[38:41]
	v_mfma_f32_16x16x32_f16 v[34:37], v[238:241], v[154:157], v[34:37]
	v_mfma_f32_16x16x32_f16 v[22:25], v[212:215], v[188:191], v[22:25]
	v_mfma_f32_16x16x32_f16 v[18:21], v[238:241], v[188:191], v[18:21]
	v_mfma_f32_16x16x32_f16 v[6:9], v[212:215], v[196:199], v[6:9]
	v_mfma_f32_16x16x32_f16 v[2:5], v[238:241], v[196:199], v[2:5]
	v_mfma_f32_16x16x32_f16 v[54:57], v[234:237], v[150:153], v[54:57]
	v_mfma_f32_16x16x32_f16 v[50:53], v[242:245], v[150:153], v[50:53]
	v_mfma_f32_16x16x32_f16 v[38:41], v[234:237], v[158:161], v[38:41]
	v_mfma_f32_16x16x32_f16 v[34:37], v[242:245], v[158:161], v[34:37]
	v_mfma_f32_16x16x32_f16 v[22:25], v[234:237], v[192:195], v[22:25]
	v_mfma_f32_16x16x32_f16 v[18:21], v[242:245], v[192:195], v[18:21]
	v_mfma_f32_16x16x32_f16 v[6:9], v[234:237], v[200:203], v[6:9]
	v_mfma_f32_16x16x32_f16 v[2:5], v[242:245], v[200:203], v[2:5]
	s_add_i32 s22, s22, 2
	s_add_u32 vcc_lo, vcc_lo, 0x100
	s_addc_u32 vcc_hi, vcc_hi, 0
	s_add_u32 s12, s12, 0x100
	s_addc_u32 s13, s13, 0
	s_cmp_gt_u32 s22, 29
	s_barrier
	s_cbranch_scc0 .LBB0_512
	s_lshl_b32 s12, s83, 8
	s_or_b32 s15, s12, s31
	v_add_u32_e32 v122, s15, v206
	v_cndmask_b32_e64 v124, 0, 1, s[44:45]
	v_ashrrev_i32_e32 v123, 31, v122
	v_mov_b32_e32 v196, 0
	v_cmp_ne_u32_e64 s[12:13], 1, v124
	s_andn2_b64 vcc, exec, s[44:45]
	v_mov_b32_e32 v124, 0
	v_mov_b32_e32 v125, 0
	s_cbranch_vccnz .LBB0_515
	v_lshlrev_b64 v[124:125], 2, v[122:123]
	v_lshl_add_u64 v[126:127], s[80:81], 0, v[124:125]
	v_lshl_add_u64 v[124:125], s[58:59], 0, v[124:125]
	global_load_dword v125, v[124:125], off
	s_nop 0
	global_load_dword v124, v[126:127], off

;     __device__ __forceinline__ void prefetch(const Unit& u, int wr, int wc, int lane) const { lnfold_prefetch(vl, stats, gW, bW, u, wr, wc, lane); }
;     __device__ __forceinline__ void prefetch(const Unit& u, int wr, int wc, int lane) const { lnfold_prefetch(vl, stats, gW, bW, u, wr, wc, lane); }
; #define PG8_STAGE(bufoff, gbase, voff) do { _Pragma("unroll") for (int _i = 0; _i < 2; ++_i) \
;         __builtin_amdgcn_global_load_lds((const unsigned*)((const char*)(gbase) + (voff)[_i]), (LAS unsigned*)(lds + (bufoff) + ldsw + _i * 8192), 16, 0, 0); } while (0)
; #define PG8_LDA(dst, b, h) do { _Pragma("unroll") for (int m = 0; m < 4; ++m) _Pragma("unroll") for (int k = 0; k < 2; ++k) dst[m][k] = *(const LAS f16x8*)(lds + PG8_SA(b, h) + aoff + m * 2048 + k * 1024); } while (0)
; #define PG8_LDB(dst, b, h) do { _Pragma("unroll") for (int n = 0; n < 2; ++n) _Pragma("unroll") for (int k = 0; k < 2; ++k) dst[n][k] = *(const LAS f16x8*)(lds + PG8_SB(b, h) + boff + n * 2048 + k * 1024); } while (0)
; #define PG8_WAIT_V(n) asm volatile("s_waitcnt vmcnt(" #n ")" ::: "memory")
; #define PG8_WAIT_L(n) asm volatile("s_waitcnt lgkmcnt(" #n ")" ::: "memory")
; #define PG8_BAR __builtin_amdgcn_s_barrier()
; template <class Epi>
; __device__ __forceinline__ void gemm_phase(LAS unsigned char* lds, const Gemm g0, const StaticOrder& S, const Epi& E) {
;     ...
;             const bool last = (t == nt - 2);
;             if (Epi::PREF && last) E.prefetch(cur, wr, wc, lane);
;             const char* a1 = cA + (size_t)(t + 1) * kstep;
;             const char* a2 = last ? nA : cA + (size_t)(t + 2) * kstep; const char* b2 = last ? nB : cB + (size_t)(t + 2) * kstep;
;             const char* a3 = a2 + kstep; const char* b3 = b2 + kstep;
;             PG8_LDB(B0, 0, 0); PG8_SCHED; PG8_LDA(At, 0, 0); PG8_STAGE(PG8_SA(1, 1), a1 + hstep, voffA);
;             PG8_WAIT_L(8); PG8_BAR; PG8_WAIT_L(0); PG8_MMA(0, 0, At, B0); PG8_BAR; PG8_SCHED;
;             PG8_LDB(B1, 0, 1); PG8_STAGE(PG8_SB(0, 0), b2, voffB);
;             PG8_BAR; PG8_WAIT_L(0); PG8_MMA(0, 1, At, B1); PG8_BAR;
;             PG8_LDA(At, 0, 1); PG8_STAGE(PG8_SA(0, 0), a2, voffA);
;             PG8_BAR; PG8_WAIT_L(0); PG8_MMA(1, 0, At, B0); PG8_BAR; PG8_SCHED;
;             PG8_STAGE(PG8_SB(0, 1), b2 + hstep, voffB);
;             PG8_WAIT_V(6); PG8_BAR; PG8_MMA(1, 1, At, B1); PG8_BAR;
.LBB0_620:
	s_add_u32 s58, s50, 0xfff80080
	s_addc_u32 s59, s51, -1
	s_and_b64 s[22:23], s[52:53], exec
	s_cselect_b32 s59, s37, s59
	s_cselect_b32 s58, s74, s58
	s_add_i32 s82, 0, 0x10000
	v_add_u32_e32 v68, s82, v189
	ds_read_b128 v[60:63], v68
	ds_read_b128 v[64:67], v68 offset:1024
	ds_read_b128 v[78:81], v68 offset:2048
	ds_read_b128 v[82:85], v68 offset:3072
	s_and_b64 s[22:23], s[52:53], exec
	s_cselect_b32 s53, s35, s25
	s_cselect_b32 s52, s75, s24
	s_add_i32 m0, s18, 0xc000
	ds_read_b128 v[86:89], v213
	ds_read_b128 v[90:93], v213 offset:1024
	ds_read_b128 v[194:197], v213 offset:2048
	ds_read_b128 v[234:237], v213 offset:3072
	ds_read_b128 v[238:241], v213 offset:4096
	ds_read_b128 v[242:245], v213 offset:5120
	ds_read_b128 v[246:249], v213 offset:6144
	ds_read_b128 v[226:229], v213 offset:7168
	global_load_lds_dwordx4 v184, s[50:51]
	s_add_i32 m0, s18, 0xe000
	s_nop 0
	global_load_lds_dwordx4 v182, s[50:51]
	s_waitcnt lgkmcnt(8)
	s_barrier
	s_waitcnt lgkmcnt(0)
	s_waitcnt lgkmcnt(0)
	v_mfma_f32_16x16x32_f16 v[158:161], v[60:63], v[86:89], v[158:161]
	v_mfma_f32_16x16x32_f16 v[150:153], v[78:81], v[86:89], v[150:153]
	v_mfma_f32_16x16x32_f16 v[142:145], v[60:63], v[194:197], v[142:145]
	v_mfma_f32_16x16x32_f16 v[134:137], v[78:81], v[194:197], v[134:137]
	v_mfma_f32_16x16x32_f16 v[126:129], v[60:63], v[238:241], v[126:129]
	v_mfma_f32_16x16x32_f16 v[118:121], v[78:81], v[238:241], v[118:121]
	v_mfma_f32_16x16x32_f16 v[110:113], v[60:63], v[246:249], v[110:113]
	v_mfma_f32_16x16x32_f16 v[102:105], v[78:81], v[246:249], v[102:105]
	v_mfma_f32_16x16x32_f16 v[158:161], v[64:67], v[90:93], v[158:161]
	v_mfma_f32_16x16x32_f16 v[150:153], v[82:85], v[90:93], v[150:153]
	v_mfma_f32_16x16x32_f16 v[142:145], v[64:67], v[234:237], v[142:145]
	v_mfma_f32_16x16x32_f16 v[134:137], v[82:85], v[234:237], v[134:137]
	v_mfma_f32_16x16x32_f16 v[126:129], v[64:67], v[242:245], v[126:129]
	v_mfma_f32_16x16x32_f16 v[118:121], v[82:85], v[242:245], v[118:121]
	v_mfma_f32_16x16x32_f16 v[110:113], v[64:67], v[226:229], v[110:113]
	v_mfma_f32_16x16x32_f16 v[102:105], v[82:85], v[226:229], v[102:105]
	s_barrier
	s_add_i32 s83, 0, 0x14000
	s_add_i32 s22, s82, s5
	v_add_u32_e32 v68, s83, v189
	v_lshl_add_u64 v[186:187], s[52:53], 0, v[178:179]
	s_mov_b32 m0, s22
	ds_read_b128 v[162:165], v68
	ds_read_b128 v[222:225], v68 offset:1024
	ds_read_b128 v[214:217], v68 offset:2048
	ds_read_b128 v[170:173], v68 offset:3072
	global_load_lds_dwordx4 v[186:187], off
	v_lshl_add_u64 v[190:191], s[52:53], 0, v[174:175]
	s_add_i32 m0, s22, 0x2000
	s_nop 0
	global_load_lds_dwordx4 v[190:191], off
	s_barrier
	s_waitcnt lgkmcnt(0)
	s_waitcnt lgkmcnt(0)
	v_mfma_f32_16x16x32_f16 v[154:157], v[162:165], v[86:89], v[154:157]
	v_mfma_f32_16x16x32_f16 v[86:89], v[214:217], v[86:89], v[146:149]
	v_mfma_f32_16x16x32_f16 v[130:133], v[214:217], v[194:197], v[130:133]
	v_mfma_f32_16x16x32_f16 v[122:125], v[162:165], v[238:241], v[122:125]
	v_mfma_f32_16x16x32_f16 v[114:117], v[214:217], v[238:241], v[114:117]
	v_mfma_f32_16x16x32_f16 v[106:109], v[162:165], v[246:249], v[106:109]
	v_mfma_f32_16x16x32_f16 v[98:101], v[214:217], v[246:249], v[98:101]
	v_mfma_f32_16x16x32_f16 v[154:157], v[222:225], v[90:93], v[154:157]
	v_mfma_f32_16x16x32_f16 v[86:89], v[170:173], v[90:93], v[86:89]
	v_mfma_f32_16x16x32_f16 v[90:93], v[162:165], v[194:197], v[138:141]
	v_mfma_f32_16x16x32_f16 v[130:133], v[170:173], v[234:237], v[130:133]
	v_mfma_f32_16x16x32_f16 v[122:125], v[222:225], v[242:245], v[122:125]
	v_mfma_f32_16x16x32_f16 v[114:117], v[170:173], v[242:245], v[114:117]
	v_mfma_f32_16x16x32_f16 v[106:109], v[222:225], v[226:229], v[106:109]
	v_mfma_f32_16x16x32_f16 v[98:101], v[170:173], v[226:229], v[98:101]
	v_mfma_f32_16x16x32_f16 v[90:93], v[222:225], v[234:237], v[90:93]
	s_mov_b32 m0, s18
	v_lshl_add_u64 v[198:199], s[58:59], 0, v[180:181]
	s_barrier
	ds_read_b128 v[138:141], v213 offset:16384
	ds_read_b128 v[146:149], v213 offset:17408
	ds_read_b128 v[194:197], v213 offset:18432
	ds_read_b128 v[226:229], v213 offset:19456
	ds_read_b128 v[234:237], v213 offset:20480
	ds_read_b128 v[238:241], v213 offset:21504
	ds_read_b128 v[242:245], v213 offset:22528
	ds_read_b128 v[246:249], v213 offset:23552
	global_load_lds_dwordx4 v[198:199], off
	v_lshl_add_u64 v[202:203], s[58:59], 0, v[176:177]
	s_mov_b32 m0, s19
	s_nop 0
	global_load_lds_dwordx4 v[202:203], off
	s_barrier
	s_waitcnt lgkmcnt(0)
	s_waitcnt lgkmcnt(0)
	v_mfma_f32_16x16x32_f16 v[94:97], v[60:63], v[138:141], v[94:97]
	v_mfma_f32_16x16x32_f16 v[68:71], v[78:81], v[138:141], v[70:73]
	v_mfma_f32_16x16x32_f16 v[46:49], v[60:63], v[194:197], v[46:49]
	v_mfma_f32_16x16x32_f16 v[38:41], v[78:81], v[194:197], v[38:41]
	v_mfma_f32_16x16x32_f16 v[30:33], v[60:63], v[234:237], v[30:33]
	v_mfma_f32_16x16x32_f16 v[22:25], v[78:81], v[234:237], v[22:25]
	v_mfma_f32_16x16x32_f16 v[14:17], v[60:63], v[242:245], v[14:17]
	v_mfma_f32_16x16x32_f16 v[6:9], v[78:81], v[242:245], v[6:9]
	v_mfma_f32_16x16x32_f16 v[94:97], v[64:67], v[146:149], v[94:97]
	v_mfma_f32_16x16x32_f16 v[68:71], v[82:85], v[146:149], v[68:71]
	v_mfma_f32_16x16x32_f16 v[46:49], v[64:67], v[226:229], v[46:49]
	v_mfma_f32_16x16x32_f16 v[38:41], v[82:85], v[226:229], v[38:41]
	v_mfma_f32_16x16x32_f16 v[30:33], v[64:67], v[238:241], v[30:33]
	v_mfma_f32_16x16x32_f16 v[22:25], v[82:85], v[238:241], v[22:25]
	v_mfma_f32_16x16x32_f16 v[14:17], v[64:67], v[246:249], v[14:17]
	v_mfma_f32_16x16x32_f16 v[6:9], v[82:85], v[246:249], v[6:9]
	s_barrier
	s_add_u32 s22, s52, 0x80000
	s_addc_u32 s23, s53, 0
	s_add_i32 s82, s83, s5
	s_mov_b32 m0, s82
	s_nop 0
	global_load_lds_dwordx4 v178, s[22:23]
	s_add_i32 m0, s82, 0x2000
	s_nop 0
	global_load_lds_dwordx4 v174, s[22:23]
	s_waitcnt vmcnt(6)
	s_barrier
; #define PG8_STAGE(bufoff, gbase, voff) do { _Pragma("unroll") for (int _i = 0; _i < 2; ++_i) \
;         __builtin_amdgcn_global_load_lds((const unsigned*)((const char*)(gbase) + (voff)[_i]), (LAS unsigned*)(lds + (bufoff) + ldsw + _i * 8192), 16, 0, 0); } while (0)
; #define PG8_LDA(dst, b, h) do { _Pragma("unroll") for (int m = 0; m < 4; ++m) _Pragma("unroll") for (int k = 0; k < 2; ++k) dst[m][k] = *(const LAS f16x8*)(lds + PG8_SA(b, h) + aoff + m * 2048 + k * 1024); } while (0)
; #define PG8_LDB(dst, b, h) do { _Pragma("unroll") for (int n = 0; n < 2; ++n) _Pragma("unroll") for (int k = 0; k < 2; ++k) dst[n][k] = *(const LAS f16x8*)(lds + PG8_SB(b, h) + boff + n * 2048 + k * 1024); } while (0)
; #define PG8_MMA(ai, bj, At, Bt) do { __builtin_amdgcn_s_setprio(1); _Pragma("unroll") for (int m = 0; m < 4; ++m) _Pragma("unroll") for (int n = 0; n < 2; ++n) _Pragma("unroll") for (int k = 0; k < 2; ++k) \
;         acc[ai][bj][m][n] = __builtin_amdgcn_mfma_f32_16x16x32_f16(Bt[n][k], At[m][k], acc[ai][bj][m][n], 0, 0, 0); __builtin_amdgcn_s_setprio(0); } while (0)
; #define PG8_WAIT_V(n) asm volatile("s_waitcnt vmcnt(" #n ")" ::: "memory")
; #define PG8_WAIT_L(n) asm volatile("s_waitcnt lgkmcnt(" #n ")" ::: "memory")
; #define PG8_BAR __builtin_amdgcn_s_barrier()
; #define PG8_SCHED __builtin_amdgcn_sched_barrier(0)
; template <class Epi>
; __device__ __forceinline__ void gemm_phase(LAS unsigned char* lds, const Gemm g0, const StaticOrder& S, const Epi& E) {
;     ...
;             PG8_WAIT_V(6); PG8_BAR; PG8_MMA(1, 1, At, B1); PG8_BAR;
;             PG8_LDB(B0, 1, 0); PG8_SCHED; PG8_LDA(At, 1, 0); PG8_STAGE(PG8_SA(0, 1), a2 + hstep, voffA);
;             PG8_WAIT_L(8); PG8_BAR; PG8_WAIT_L(0); PG8_MMA(0, 0, At, B0); PG8_BAR; PG8_SCHED;
;             PG8_LDB(B1, 1, 1); PG8_STAGE(PG8_SB(1, 0), b3, voffB);
;             PG8_BAR; PG8_WAIT_L(0); PG8_MMA(0, 1, At, B1); PG8_BAR;
	v_mfma_f32_16x16x32_f16 v[50:53], v[214:217], v[138:141], v[50:53]
	v_mfma_f32_16x16x32_f16 v[42:45], v[162:165], v[194:197], v[42:45]
	v_mfma_f32_16x16x32_f16 v[34:37], v[214:217], v[194:197], v[34:37]
	v_mfma_f32_16x16x32_f16 v[26:29], v[162:165], v[234:237], v[26:29]
	v_mfma_f32_16x16x32_f16 v[18:21], v[214:217], v[234:237], v[18:21]
	v_mfma_f32_16x16x32_f16 v[10:13], v[162:165], v[242:245], v[10:13]
	v_mfma_f32_16x16x32_f16 v[2:5], v[214:217], v[242:245], v[2:5]
	v_mfma_f32_16x16x32_f16 v[60:63], v[162:165], v[138:141], v[74:77]
	v_mfma_f32_16x16x32_f16 v[50:53], v[170:173], v[146:149], v[50:53]
	v_mfma_f32_16x16x32_f16 v[42:45], v[222:225], v[226:229], v[42:45]
	v_mfma_f32_16x16x32_f16 v[34:37], v[170:173], v[226:229], v[34:37]
	v_mfma_f32_16x16x32_f16 v[26:29], v[222:225], v[238:241], v[26:29]
	v_mfma_f32_16x16x32_f16 v[18:21], v[170:173], v[238:241], v[18:21]
	v_mfma_f32_16x16x32_f16 v[10:13], v[222:225], v[246:249], v[10:13]
	v_mfma_f32_16x16x32_f16 v[2:5], v[170:173], v[246:249], v[2:5]
	v_mfma_f32_16x16x32_f16 v[60:63], v[222:225], v[146:149], v[60:63]
	s_add_i32 s82, 0, 0x18000
	v_add_u32_e32 v72, s82, v189
	s_barrier
	ds_read_b128 v[64:67], v72
	ds_read_b128 v[74:77], v72 offset:1024
	ds_read_b128 v[78:81], v72 offset:2048
	ds_read_b128 v[82:85], v72 offset:3072
	s_add_u32 s22, s58, 0x80000
	s_addc_u32 s23, s59, 0
	s_mov_b32 m0, s28
	ds_read_b128 v[138:141], v213 offset:32768
	ds_read_b128 v[146:149], v213 offset:33792
	ds_read_b128 v[162:165], v213 offset:34816
	ds_read_b128 v[170:173], v213 offset:35840
	ds_read_b128 v[194:197], v213 offset:36864
	ds_read_b128 v[214:217], v213 offset:37888
	ds_read_b128 v[222:225], v213 offset:38912
	ds_read_b128 v[226:229], v213 offset:39936
	global_load_lds_dwordx4 v180, s[22:23]
	s_mov_b32 m0, s29
	s_nop 0
	global_load_lds_dwordx4 v176, s[22:23]
	s_waitcnt lgkmcnt(8)
	s_barrier
	s_waitcnt lgkmcnt(0)
	s_waitcnt lgkmcnt(0)
	v_mfma_f32_16x16x32_f16 v[158:161], v[64:67], v[138:141], v[158:161]
	v_mfma_f32_16x16x32_f16 v[150:153], v[78:81], v[138:141], v[150:153]
	v_mfma_f32_16x16x32_f16 v[142:145], v[64:67], v[162:165], v[142:145]
	v_mfma_f32_16x16x32_f16 v[134:137], v[78:81], v[162:165], v[134:137]
	v_mfma_f32_16x16x32_f16 v[126:129], v[64:67], v[194:197], v[126:129]
	v_mfma_f32_16x16x32_f16 v[118:121], v[78:81], v[194:197], v[118:121]
	v_mfma_f32_16x16x32_f16 v[110:113], v[64:67], v[222:225], v[110:113]
	v_mfma_f32_16x16x32_f16 v[102:105], v[78:81], v[222:225], v[102:105]
	v_mfma_f32_16x16x32_f16 v[158:161], v[74:77], v[146:149], v[158:161]
	v_mfma_f32_16x16x32_f16 v[150:153], v[82:85], v[146:149], v[150:153]
	v_mfma_f32_16x16x32_f16 v[142:145], v[74:77], v[170:173], v[142:145]
	v_mfma_f32_16x16x32_f16 v[134:137], v[82:85], v[170:173], v[134:137]
	v_mfma_f32_16x16x32_f16 v[126:129], v[74:77], v[214:217], v[126:129]
	v_mfma_f32_16x16x32_f16 v[118:121], v[82:85], v[214:217], v[118:121]
	v_mfma_f32_16x16x32_f16 v[110:113], v[74:77], v[226:229], v[110:113]
	v_mfma_f32_16x16x32_f16 v[102:105], v[82:85], v[226:229], v[102:105]
	s_barrier
	s_add_i32 s58, 0, 0x1c000
	v_add_u32_e32 v72, s58, v189
	s_add_i32 s22, s82, s5
	ds_read_b128 v[234:237], v72
	ds_read_b128 v[238:241], v72 offset:1024
	ds_read_b128 v[242:245], v72 offset:2048
	ds_read_b128 v[246:249], v72 offset:3072
	v_lshl_add_u64 v[72:73], v[186:187], 0, s[64:65]
	s_mov_b32 m0, s22
	s_nop 0
	global_load_lds_dwordx4 v[72:73], off
	v_lshl_add_u64 v[72:73], v[190:191], 0, s[64:65]
	s_add_i32 m0, s22, 0x2000
	s_nop 0
	global_load_lds_dwordx4 v[72:73], off
	s_barrier
; #define PG8_STAGE(bufoff, gbase, voff) do { _Pragma("unroll") for (int _i = 0; _i < 2; ++_i) \
;         __builtin_amdgcn_global_load_lds((const unsigned*)((const char*)(gbase) + (voff)[_i]), (LAS unsigned*)(lds + (bufoff) + ldsw + _i * 8192), 16, 0, 0); } while (0)
; #define PG8_LDA(dst, b, h) do { _Pragma("unroll") for (int m = 0; m < 4; ++m) _Pragma("unroll") for (int k = 0; k < 2; ++k) dst[m][k] = *(const LAS f16x8*)(lds + PG8_SA(b, h) + aoff + m * 2048 + k * 1024); } while (0)
; #define PG8_MMA(ai, bj, At, Bt) do { __builtin_amdgcn_s_setprio(1); _Pragma("unroll") for (int m = 0; m < 4; ++m) _Pragma("unroll") for (int n = 0; n < 2; ++n) _Pragma("unroll") for (int k = 0; k < 2; ++k) \
;         acc[ai][bj][m][n] = __builtin_amdgcn_mfma_f32_16x16x32_f16(Bt[n][k], At[m][k], acc[ai][bj][m][n], 0, 0, 0); __builtin_amdgcn_s_setprio(0); } while (0)
; #define PG8_WAIT_V(n) asm volatile("s_waitcnt vmcnt(" #n ")" ::: "memory")
; #define PG8_WAIT_L(n) asm volatile("s_waitcnt lgkmcnt(" #n ")" ::: "memory")
; #define PG8_BAR __builtin_amdgcn_s_barrier()
; #define PG8_SCHED __builtin_amdgcn_sched_barrier(0)
; template <class Epi>
; __device__ __forceinline__ void gemm_phase(LAS unsigned char* lds, const Gemm g0, const StaticOrder& S, const Epi& E) {
;     ...
;             PG8_BAR; PG8_WAIT_L(0); PG8_MMA(0, 1, At, B1); PG8_BAR;
;             PG8_LDA(At, 1, 1); PG8_STAGE(PG8_SA(1, 0), a3, voffA);
;             PG8_BAR; PG8_WAIT_L(0); PG8_MMA(1, 0, At, B0); PG8_BAR; PG8_SCHED;
;             PG8_STAGE(PG8_SB(1, 1), b3 + hstep, voffB);
;             PG8_WAIT_V(6); PG8_BAR; PG8_MMA(1, 1, At, B1); PG8_BAR;
;         }
	s_waitcnt lgkmcnt(0)
	s_waitcnt lgkmcnt(0)
	v_mfma_f32_16x16x32_f16 v[154:157], v[234:237], v[138:141], v[154:157]
	v_mfma_f32_16x16x32_f16 v[86:89], v[242:245], v[138:141], v[86:89]
	v_mfma_f32_16x16x32_f16 v[154:157], v[238:241], v[146:149], v[154:157]
	v_mfma_f32_16x16x32_f16 v[146:149], v[246:249], v[146:149], v[86:89]
	v_mfma_f32_16x16x32_f16 v[86:89], v[234:237], v[162:165], v[90:93]
	v_mfma_f32_16x16x32_f16 v[138:141], v[238:241], v[170:173], v[86:89]
	v_mfma_f32_16x16x32_f16 v[86:89], v[242:245], v[162:165], v[130:133]
	v_mfma_f32_16x16x32_f16 v[130:133], v[246:249], v[170:173], v[86:89]
	v_mfma_f32_16x16x32_f16 v[86:89], v[234:237], v[194:197], v[122:125]
	v_mfma_f32_16x16x32_f16 v[122:125], v[238:241], v[214:217], v[86:89]
	v_mfma_f32_16x16x32_f16 v[86:89], v[242:245], v[194:197], v[114:117]
	v_mfma_f32_16x16x32_f16 v[114:117], v[246:249], v[214:217], v[86:89]
	v_mfma_f32_16x16x32_f16 v[86:89], v[234:237], v[222:225], v[106:109]
	v_mfma_f32_16x16x32_f16 v[106:109], v[238:241], v[226:229], v[86:89]
	v_mfma_f32_16x16x32_f16 v[86:89], v[242:245], v[222:225], v[98:101]
	v_mfma_f32_16x16x32_f16 v[98:101], v[246:249], v[226:229], v[86:89]
	s_mov_b32 m0, s31
	v_lshl_add_u64 v[72:73], v[198:199], 0, s[64:65]
	s_barrier
	s_nop 2
	ds_read_b128 v[86:89], v213 offset:49152
	ds_read_b128 v[90:93], v213 offset:50176
	ds_read_b128 v[162:165], v213 offset:51200
	ds_read_b128 v[170:173], v213 offset:52224
	ds_read_b128 v[194:197], v213 offset:53248
	ds_read_b128 v[214:217], v213 offset:54272
	ds_read_b128 v[222:225], v213 offset:55296
	ds_read_b128 v[226:229], v213 offset:56320
	global_load_lds_dwordx4 v[72:73], off
	v_lshl_add_u64 v[72:73], v[202:203], 0, s[64:65]
	s_mov_b32 m0, s61
	s_nop 0
	global_load_lds_dwordx4 v[72:73], off
	s_barrier
	s_waitcnt lgkmcnt(0)
	s_waitcnt lgkmcnt(0)
	v_mfma_f32_16x16x32_f16 v[94:97], v[64:67], v[86:89], v[94:97]
	v_mfma_f32_16x16x32_f16 v[68:71], v[78:81], v[86:89], v[68:71]
	v_mfma_f32_16x16x32_f16 v[46:49], v[64:67], v[162:165], v[46:49]
	v_mfma_f32_16x16x32_f16 v[38:41], v[78:81], v[162:165], v[38:41]
	v_mfma_f32_16x16x32_f16 v[30:33], v[64:67], v[194:197], v[30:33]
	v_mfma_f32_16x16x32_f16 v[22:25], v[78:81], v[194:197], v[22:25]
	v_mfma_f32_16x16x32_f16 v[14:17], v[64:67], v[222:225], v[14:17]
	v_mfma_f32_16x16x32_f16 v[6:9], v[78:81], v[222:225], v[6:9]
	v_mfma_f32_16x16x32_f16 v[94:97], v[74:77], v[90:93], v[94:97]
	v_mfma_f32_16x16x32_f16 v[70:73], v[82:85], v[90:93], v[68:71]
	v_mfma_f32_16x16x32_f16 v[46:49], v[74:77], v[170:173], v[46:49]
	v_mfma_f32_16x16x32_f16 v[38:41], v[82:85], v[170:173], v[38:41]
	v_mfma_f32_16x16x32_f16 v[30:33], v[74:77], v[214:217], v[30:33]
	v_mfma_f32_16x16x32_f16 v[22:25], v[82:85], v[214:217], v[22:25]
	v_mfma_f32_16x16x32_f16 v[14:17], v[74:77], v[226:229], v[14:17]
	v_mfma_f32_16x16x32_f16 v[6:9], v[82:85], v[226:229], v[6:9]
	s_barrier
	s_add_u32 s22, s52, 0x80080
	s_addc_u32 s23, s53, 0
	s_add_i32 s52, s58, s5
	s_mov_b32 m0, s52
	s_nop 0
	global_load_lds_dwordx4 v178, s[22:23]
	v_lshl_add_u64 v[64:65], s[22:23], 0, v[174:175]
	s_add_i32 m0, s52, 0x2000
	s_nop 0
	global_load_lds_dwordx4 v[64:65], off
	s_waitcnt vmcnt(6)
	s_barrier
	v_mfma_f32_16x16x32_f16 v[60:63], v[234:237], v[86:89], v[60:63]
	v_mfma_f32_16x16x32_f16 v[50:53], v[242:245], v[86:89], v[50:53]
	v_mfma_f32_16x16x32_f16 v[42:45], v[234:237], v[162:165], v[42:45]
	v_mfma_f32_16x16x32_f16 v[34:37], v[242:245], v[162:165], v[34:37]
	v_mfma_f32_16x16x32_f16 v[26:29], v[234:237], v[194:197], v[26:29]
	v_mfma_f32_16x16x32_f16 v[18:21], v[242:245], v[194:197], v[18:21]
	v_mfma_f32_16x16x32_f16 v[10:13], v[234:237], v[222:225], v[10:13]
	v_mfma_f32_16x16x32_f16 v[2:5], v[242:245], v[222:225], v[2:5]
	v_mfma_f32_16x16x32_f16 v[74:77], v[238:241], v[90:93], v[60:63]
	v_mfma_f32_16x16x32_f16 v[50:53], v[246:249], v[90:93], v[50:53]
	v_mfma_f32_16x16x32_f16 v[42:45], v[238:241], v[170:173], v[42:45]
	v_mfma_f32_16x16x32_f16 v[34:37], v[246:249], v[170:173], v[34:37]
	v_mfma_f32_16x16x32_f16 v[26:29], v[238:241], v[214:217], v[26:29]
	v_mfma_f32_16x16x32_f16 v[18:21], v[246:249], v[214:217], v[18:21]
	v_mfma_f32_16x16x32_f16 v[10:13], v[238:241], v[226:229], v[10:13]
	v_mfma_f32_16x16x32_f16 v[2:5], v[246:249], v[226:229], v[2:5]
	s_add_i32 s81, s81, 2
	s_add_u32 s24, s24, 0x100
	s_addc_u32 s25, s25, 0
	s_add_u32 s50, s50, 0x100
	s_addc_u32 s51, s51, 0
	s_cmp_gt_u32 s81, 29
	s_barrier
	s_cbranch_scc1 .LBB0_616

;     __device__ __forceinline__ void prefetch(const Unit& u, int wr, int wc, int lane) const { lnfold_prefetch(vl, stats, gW, bW, u, wr, wc, lane); }
;     __device__ __forceinline__ void prefetch(const Unit& u, int wr, int wc, int lane) const { lnfold_prefetch(vl, stats, gW, bW, u, wr, wc, lane); }
; #define PG8_STAGE(bufoff, gbase, voff) do { _Pragma("unroll") for (int _i = 0; _i < 2; ++_i) \
;         __builtin_amdgcn_global_load_lds((const unsigned*)((const char*)(gbase) + (voff)[_i]), (LAS unsigned*)(lds + (bufoff) + ldsw + _i * 8192), 16, 0, 0); } while (0)
; #define PG8_LDA(dst, b, h) do { _Pragma("unroll") for (int m = 0; m < 4; ++m) _Pragma("unroll") for (int k = 0; k < 2; ++k) dst[m][k] = *(const LAS f16x8*)(lds + PG8_SA(b, h) + aoff + m * 2048 + k * 1024); } while (0)
; #define PG8_LDB(dst, b, h) do { _Pragma("unroll") for (int n = 0; n < 2; ++n) _Pragma("unroll") for (int k = 0; k < 2; ++k) dst[n][k] = *(const LAS f16x8*)(lds + PG8_SB(b, h) + boff + n * 2048 + k * 1024); } while (0)
; #define PG8_WAIT_V(n) asm volatile("s_waitcnt vmcnt(" #n ")" ::: "memory")
; #define PG8_WAIT_L(n) asm volatile("s_waitcnt lgkmcnt(" #n ")" ::: "memory")
; #define PG8_BAR __builtin_amdgcn_s_barrier()
; template <class Epi>
; __device__ __forceinline__ void gemm_phase(LAS unsigned char* lds, const Gemm g0, const StaticOrder& S, const Epi& E) {
;     ...
;             const bool last = (t == nt - 2);
;             if (Epi::PREF && last) E.prefetch(cur, wr, wc, lane);
;             const char* a1 = cA + (size_t)(t + 1) * kstep;
;             const char* a2 = last ? nA : cA + (size_t)(t + 2) * kstep; const char* b2 = last ? nB : cB + (size_t)(t + 2) * kstep;
;             const char* a3 = a2 + kstep; const char* b3 = b2 + kstep;
;             PG8_LDB(B0, 0, 0); PG8_SCHED; PG8_LDA(At, 0, 0); PG8_STAGE(PG8_SA(1, 1), a1 + hstep, voffA);
;             PG8_WAIT_L(8); PG8_BAR; PG8_WAIT_L(0); PG8_MMA(0, 0, At, B0); PG8_BAR; PG8_SCHED;
;             PG8_LDB(B1, 0, 1); PG8_STAGE(PG8_SB(0, 0), b2, voffB);
;             PG8_BAR; PG8_WAIT_L(0); PG8_MMA(0, 1, At, B1); PG8_BAR;
;             PG8_LDA(At, 0, 1); PG8_STAGE(PG8_SA(0, 0), a2, voffA);
;             PG8_BAR; PG8_WAIT_L(0); PG8_MMA(1, 0, At, B0); PG8_BAR; PG8_SCHED;
;             PG8_STAGE(PG8_SB(0, 1), b2 + hstep, voffB);
;             PG8_WAIT_V(6); PG8_BAR; PG8_MMA(1, 1, At, B1); PG8_BAR;
.LBB0_672:
	s_add_u32 s10, s12, 0x100
	s_addc_u32 s11, s13, 0
	s_add_i32 s23, 0, 0x10000
	v_add_u32_e32 v142, s23, v203
	ds_read_b128 v[130:133], v142
	ds_read_b128 v[134:137], v142 offset:1024
	ds_read_b128 v[138:141], v142 offset:2048
	ds_read_b128 v[142:145], v142 offset:3072
	s_cmpk_eq_i32 s22, 0x54
	s_cselect_b32 s81, s1, s11
	s_cselect_b32 s80, s0, s10
	s_cselect_b32 s63, s59, s25
	s_cselect_b32 s62, s58, s24
	s_add_i32 m0, s28, 0xc000
	ds_read_b128 v[146:149], v208
	ds_read_b128 v[150:153], v208 offset:1024
	ds_read_b128 v[154:157], v208 offset:2048
	ds_read_b128 v[162:165], v208 offset:3072
	ds_read_b128 v[170:173], v208 offset:4096
	ds_read_b128 v[184:187], v208 offset:5120
	ds_read_b128 v[188:191], v208 offset:6144
	ds_read_b128 v[192:195], v208 offset:7168
	global_load_lds_dwordx4 v182, s[12:13]
	s_add_i32 m0, s28, 0xe000
	s_nop 0
	global_load_lds_dwordx4 v180, s[12:13]
	s_waitcnt lgkmcnt(8)
	s_barrier
	s_waitcnt lgkmcnt(0)
	s_waitcnt lgkmcnt(0)
	v_mfma_f32_16x16x32_f16 v[126:129], v[130:133], v[146:149], v[126:129]
	v_mfma_f32_16x16x32_f16 v[122:125], v[138:141], v[146:149], v[122:125]
	v_mfma_f32_16x16x32_f16 v[110:113], v[130:133], v[154:157], v[110:113]
	v_mfma_f32_16x16x32_f16 v[106:109], v[138:141], v[154:157], v[106:109]
	v_mfma_f32_16x16x32_f16 v[94:97], v[130:133], v[170:173], v[94:97]
	v_mfma_f32_16x16x32_f16 v[90:93], v[138:141], v[170:173], v[90:93]
	v_mfma_f32_16x16x32_f16 v[78:81], v[130:133], v[188:191], v[78:81]
	v_mfma_f32_16x16x32_f16 v[74:77], v[138:141], v[188:191], v[74:77]
	v_mfma_f32_16x16x32_f16 v[126:129], v[134:137], v[150:153], v[126:129]
	v_mfma_f32_16x16x32_f16 v[122:125], v[142:145], v[150:153], v[122:125]
	v_mfma_f32_16x16x32_f16 v[110:113], v[134:137], v[162:165], v[110:113]
	v_mfma_f32_16x16x32_f16 v[106:109], v[142:145], v[162:165], v[106:109]
	v_mfma_f32_16x16x32_f16 v[94:97], v[134:137], v[184:187], v[94:97]
	v_mfma_f32_16x16x32_f16 v[90:93], v[142:145], v[184:187], v[90:93]
	v_mfma_f32_16x16x32_f16 v[78:81], v[134:137], v[192:195], v[78:81]
	v_mfma_f32_16x16x32_f16 v[74:77], v[142:145], v[192:195], v[74:77]
	s_barrier
	s_add_i32 s90, 0, 0x14000
	v_add_u32_e32 v200, s90, v203
	s_add_i32 s12, s23, s19
	ds_read_b128 v[196:199], v200
	ds_read_b128 v[210:213], v200 offset:1024
	ds_read_b128 v[214:217], v200 offset:2048
	ds_read_b128 v[222:225], v200 offset:3072
	v_lshl_add_u64 v[200:201], s[62:63], 0, v[174:175]
	s_mov_b32 m0, s12
	v_lshl_add_u64 v[218:219], s[62:63], 0, v[158:159]
	global_load_lds_dwordx4 v[200:201], off
	s_add_i32 m0, s12, 0x2000
	s_nop 0
	global_load_lds_dwordx4 v[218:219], off
	s_barrier
	s_waitcnt lgkmcnt(0)
	s_waitcnt lgkmcnt(0)
	v_mfma_f32_16x16x32_f16 v[118:121], v[196:199], v[146:149], v[118:121]
	v_mfma_f32_16x16x32_f16 v[114:117], v[214:217], v[146:149], v[114:117]
	v_mfma_f32_16x16x32_f16 v[102:105], v[196:199], v[154:157], v[102:105]
	v_mfma_f32_16x16x32_f16 v[98:101], v[214:217], v[154:157], v[98:101]
	v_mfma_f32_16x16x32_f16 v[86:89], v[196:199], v[170:173], v[86:89]
	v_mfma_f32_16x16x32_f16 v[82:85], v[214:217], v[170:173], v[82:85]
	v_mfma_f32_16x16x32_f16 v[70:73], v[196:199], v[188:191], v[70:73]
	v_mfma_f32_16x16x32_f16 v[66:69], v[214:217], v[188:191], v[66:69]
	v_mfma_f32_16x16x32_f16 v[118:121], v[210:213], v[150:153], v[118:121]
	v_mfma_f32_16x16x32_f16 v[114:117], v[222:225], v[150:153], v[114:117]
	v_mfma_f32_16x16x32_f16 v[102:105], v[210:213], v[162:165], v[102:105]
	v_mfma_f32_16x16x32_f16 v[98:101], v[222:225], v[162:165], v[98:101]
	v_mfma_f32_16x16x32_f16 v[86:89], v[210:213], v[184:187], v[86:89]
	v_mfma_f32_16x16x32_f16 v[82:85], v[222:225], v[184:187], v[82:85]
	v_mfma_f32_16x16x32_f16 v[70:73], v[210:213], v[192:195], v[70:73]
	v_mfma_f32_16x16x32_f16 v[66:69], v[222:225], v[192:195], v[66:69]
	s_mov_b32 m0, s28
	v_lshl_add_u64 v[226:227], s[80:81], 0, v[176:177]
	s_barrier
	ds_read_b128 v[146:149], v208 offset:16384
	ds_read_b128 v[150:153], v208 offset:17408
	ds_read_b128 v[154:157], v208 offset:18432
	ds_read_b128 v[162:165], v208 offset:19456
	ds_read_b128 v[170:173], v208 offset:20480
	ds_read_b128 v[184:187], v208 offset:21504
	ds_read_b128 v[188:191], v208 offset:22528
	ds_read_b128 v[192:195], v208 offset:23552
	global_load_lds_dwordx4 v[226:227], off
	v_lshl_add_u64 v[228:229], s[80:81], 0, v[160:161]
	s_mov_b32 m0, s29
	s_nop 0
	global_load_lds_dwordx4 v[228:229], off
	s_barrier
	s_waitcnt lgkmcnt(0)
	s_waitcnt lgkmcnt(0)
	v_mfma_f32_16x16x32_f16 v[62:65], v[130:133], v[146:149], v[62:65]
	v_mfma_f32_16x16x32_f16 v[58:61], v[138:141], v[146:149], v[58:61]
	v_mfma_f32_16x16x32_f16 v[46:49], v[130:133], v[154:157], v[46:49]
	v_mfma_f32_16x16x32_f16 v[42:45], v[138:141], v[154:157], v[42:45]
	v_mfma_f32_16x16x32_f16 v[30:33], v[130:133], v[170:173], v[30:33]
	v_mfma_f32_16x16x32_f16 v[26:29], v[138:141], v[170:173], v[26:29]
	v_mfma_f32_16x16x32_f16 v[14:17], v[130:133], v[188:191], v[14:17]
	v_mfma_f32_16x16x32_f16 v[10:13], v[138:141], v[188:191], v[10:13]
	v_mfma_f32_16x16x32_f16 v[62:65], v[134:137], v[150:153], v[62:65]
	v_mfma_f32_16x16x32_f16 v[58:61], v[142:145], v[150:153], v[58:61]
	v_mfma_f32_16x16x32_f16 v[46:49], v[134:137], v[162:165], v[46:49]
	v_mfma_f32_16x16x32_f16 v[42:45], v[142:145], v[162:165], v[42:45]
	v_mfma_f32_16x16x32_f16 v[30:33], v[134:137], v[184:187], v[30:33]
	v_mfma_f32_16x16x32_f16 v[26:29], v[142:145], v[184:187], v[26:29]
	v_mfma_f32_16x16x32_f16 v[14:17], v[134:137], v[192:195], v[14:17]
	v_mfma_f32_16x16x32_f16 v[10:13], v[142:145], v[192:195], v[10:13]
	s_barrier
	s_add_u32 s12, s62, 0x160000
	s_addc_u32 s13, s63, 0
	s_add_i32 s23, s90, s19
	s_mov_b32 m0, s23
	s_nop 0
	global_load_lds_dwordx4 v174, s[12:13]
	s_add_i32 m0, s23, 0x2000
	s_nop 0
	global_load_lds_dwordx4 v158, s[12:13]
	s_waitcnt vmcnt(6)
	s_barrier
; #define PG8_STAGE(bufoff, gbase, voff) do { _Pragma("unroll") for (int _i = 0; _i < 2; ++_i) \
;         __builtin_amdgcn_global_load_lds((const unsigned*)((const char*)(gbase) + (voff)[_i]), (LAS unsigned*)(lds + (bufoff) + ldsw + _i * 8192), 16, 0, 0); } while (0)
; #define PG8_LDA(dst, b, h) do { _Pragma("unroll") for (int m = 0; m < 4; ++m) _Pragma("unroll") for (int k = 0; k < 2; ++k) dst[m][k] = *(const LAS f16x8*)(lds + PG8_SA(b, h) + aoff + m * 2048 + k * 1024); } while (0)
; #define PG8_LDB(dst, b, h) do { _Pragma("unroll") for (int n = 0; n < 2; ++n) _Pragma("unroll") for (int k = 0; k < 2; ++k) dst[n][k] = *(const LAS f16x8*)(lds + PG8_SB(b, h) + boff + n * 2048 + k * 1024); } while (0)
; #define PG8_MMA(ai, bj, At, Bt) do { __builtin_amdgcn_s_setprio(1); _Pragma("unroll") for (int m = 0; m < 4; ++m) _Pragma("unroll") for (int n = 0; n < 2; ++n) _Pragma("unroll") for (int k = 0; k < 2; ++k) \
;         acc[ai][bj][m][n] = __builtin_amdgcn_mfma_f32_16x16x32_f16(Bt[n][k], At[m][k], acc[ai][bj][m][n], 0, 0, 0); __builtin_amdgcn_s_setprio(0); } while (0)
; #define PG8_WAIT_V(n) asm volatile("s_waitcnt vmcnt(" #n ")" ::: "memory")
; #define PG8_WAIT_L(n) asm volatile("s_waitcnt lgkmcnt(" #n ")" ::: "memory")
; #define PG8_BAR __builtin_amdgcn_s_barrier()
; #define PG8_SCHED __builtin_amdgcn_sched_barrier(0)
; template <class Epi>
; __device__ __forceinline__ void gemm_phase(LAS unsigned char* lds, const Gemm g0, const StaticOrder& S, const Epi& E) {
;     ...
;             PG8_WAIT_V(6); PG8_BAR; PG8_MMA(1, 1, At, B1); PG8_BAR;
;             PG8_LDB(B0, 1, 0); PG8_SCHED; PG8_LDA(At, 1, 0); PG8_STAGE(PG8_SA(0, 1), a2 + hstep, voffA);
;             PG8_WAIT_L(8); PG8_BAR; PG8_WAIT_L(0); PG8_MMA(0, 0, At, B0); PG8_BAR; PG8_SCHED;
;             PG8_LDB(B1, 1, 1); PG8_STAGE(PG8_SB(1, 0), b3, voffB);
;             PG8_BAR; PG8_WAIT_L(0); PG8_MMA(0, 1, At, B1); PG8_BAR;
;             PG8_LDA(At, 1, 1); PG8_STAGE(PG8_SA(1, 0), a3, voffA);
	v_mfma_f32_16x16x32_f16 v[54:57], v[196:199], v[146:149], v[54:57]
	v_mfma_f32_16x16x32_f16 v[50:53], v[214:217], v[146:149], v[50:53]
	v_mfma_f32_16x16x32_f16 v[38:41], v[196:199], v[154:157], v[38:41]
	v_mfma_f32_16x16x32_f16 v[34:37], v[214:217], v[154:157], v[34:37]
	v_mfma_f32_16x16x32_f16 v[22:25], v[196:199], v[170:173], v[22:25]
	v_mfma_f32_16x16x32_f16 v[18:21], v[214:217], v[170:173], v[18:21]
	v_mfma_f32_16x16x32_f16 v[6:9], v[196:199], v[188:191], v[6:9]
	v_mfma_f32_16x16x32_f16 v[2:5], v[214:217], v[188:191], v[2:5]
	v_mfma_f32_16x16x32_f16 v[54:57], v[210:213], v[150:153], v[54:57]
	v_mfma_f32_16x16x32_f16 v[50:53], v[222:225], v[150:153], v[50:53]
	v_mfma_f32_16x16x32_f16 v[38:41], v[210:213], v[162:165], v[38:41]
	v_mfma_f32_16x16x32_f16 v[34:37], v[222:225], v[162:165], v[34:37]
	v_mfma_f32_16x16x32_f16 v[22:25], v[210:213], v[184:187], v[22:25]
	v_mfma_f32_16x16x32_f16 v[18:21], v[222:225], v[184:187], v[18:21]
	v_mfma_f32_16x16x32_f16 v[6:9], v[210:213], v[192:195], v[6:9]
	v_mfma_f32_16x16x32_f16 v[2:5], v[222:225], v[192:195], v[2:5]
	s_add_i32 s23, 0, 0x18000
	v_add_u32_e32 v142, s23, v203
	s_barrier
	ds_read_b128 v[130:133], v142
	ds_read_b128 v[134:137], v142 offset:1024
	ds_read_b128 v[138:141], v142 offset:2048
	ds_read_b128 v[142:145], v142 offset:3072
	s_add_u32 s12, s80, 0x160000
	s_addc_u32 s13, s81, 0
	s_mov_b32 m0, s31
	ds_read_b128 v[146:149], v208 offset:32768
	ds_read_b128 v[150:153], v208 offset:33792
	ds_read_b128 v[154:157], v208 offset:34816
	ds_read_b128 v[162:165], v208 offset:35840
	ds_read_b128 v[170:173], v208 offset:36864
	ds_read_b128 v[184:187], v208 offset:37888
	ds_read_b128 v[188:191], v208 offset:38912
	ds_read_b128 v[192:195], v208 offset:39936
	global_load_lds_dwordx4 v176, s[12:13]
	s_mov_b32 m0, s61
	s_nop 0
	global_load_lds_dwordx4 v160, s[12:13]
	s_waitcnt lgkmcnt(8)
	s_barrier
	s_waitcnt lgkmcnt(0)
	s_waitcnt lgkmcnt(0)
	v_mfma_f32_16x16x32_f16 v[126:129], v[130:133], v[146:149], v[126:129]
	v_mfma_f32_16x16x32_f16 v[122:125], v[138:141], v[146:149], v[122:125]
	v_mfma_f32_16x16x32_f16 v[110:113], v[130:133], v[154:157], v[110:113]
	v_mfma_f32_16x16x32_f16 v[106:109], v[138:141], v[154:157], v[106:109]
	v_mfma_f32_16x16x32_f16 v[94:97], v[130:133], v[170:173], v[94:97]
	v_mfma_f32_16x16x32_f16 v[90:93], v[138:141], v[170:173], v[90:93]
	v_mfma_f32_16x16x32_f16 v[78:81], v[130:133], v[188:191], v[78:81]
	v_mfma_f32_16x16x32_f16 v[74:77], v[138:141], v[188:191], v[74:77]
	v_mfma_f32_16x16x32_f16 v[126:129], v[134:137], v[150:153], v[126:129]
	v_mfma_f32_16x16x32_f16 v[122:125], v[142:145], v[150:153], v[122:125]
	v_mfma_f32_16x16x32_f16 v[110:113], v[134:137], v[162:165], v[110:113]
	v_mfma_f32_16x16x32_f16 v[106:109], v[142:145], v[162:165], v[106:109]
	v_mfma_f32_16x16x32_f16 v[94:97], v[134:137], v[184:187], v[94:97]
	v_mfma_f32_16x16x32_f16 v[90:93], v[142:145], v[184:187], v[90:93]
	v_mfma_f32_16x16x32_f16 v[78:81], v[134:137], v[192:195], v[78:81]
	v_mfma_f32_16x16x32_f16 v[74:77], v[142:145], v[192:195], v[74:77]
	s_barrier
	s_add_i32 s80, 0, 0x1c000
	s_add_i32 s12, s23, s19
	v_add_u32_e32 v209, s80, v203
	v_lshl_add_u64 v[200:201], v[200:201], 0, s[64:65]
	s_mov_b32 m0, s12
	ds_read_b128 v[196:199], v209
	ds_read_b128 v[210:213], v209 offset:1024
	ds_read_b128 v[214:217], v209 offset:2048
	ds_read_b128 v[222:225], v209 offset:3072
	global_load_lds_dwordx4 v[200:201], off
	v_lshl_add_u64 v[200:201], v[218:219], 0, s[64:65]
	s_add_i32 m0, s12, 0x2000
	s_nop 0
	global_load_lds_dwordx4 v[200:201], off
	s_barrier
	s_waitcnt lgkmcnt(0)
	s_waitcnt lgkmcnt(0)
	v_mfma_f32_16x16x32_f16 v[118:121], v[196:199], v[146:149], v[118:121]
	v_mfma_f32_16x16x32_f16 v[114:117], v[214:217], v[146:149], v[114:117]
	v_mfma_f32_16x16x32_f16 v[102:105], v[196:199], v[154:157], v[102:105]
	v_mfma_f32_16x16x32_f16 v[98:101], v[214:217], v[154:157], v[98:101]
	v_mfma_f32_16x16x32_f16 v[86:89], v[196:199], v[170:173], v[86:89]
	v_mfma_f32_16x16x32_f16 v[82:85], v[214:217], v[170:173], v[82:85]
	v_mfma_f32_16x16x32_f16 v[70:73], v[196:199], v[188:191], v[70:73]
	v_mfma_f32_16x16x32_f16 v[66:69], v[214:217], v[188:191], v[66:69]
	v_mfma_f32_16x16x32_f16 v[118:121], v[210:213], v[150:153], v[118:121]
	v_mfma_f32_16x16x32_f16 v[114:117], v[222:225], v[150:153], v[114:117]
	v_mfma_f32_16x16x32_f16 v[102:105], v[210:213], v[162:165], v[102:105]
	v_mfma_f32_16x16x32_f16 v[98:101], v[222:225], v[162:165], v[98:101]
	v_mfma_f32_16x16x32_f16 v[86:89], v[210:213], v[184:187], v[86:89]
	v_mfma_f32_16x16x32_f16 v[82:85], v[222:225], v[184:187], v[82:85]
	v_mfma_f32_16x16x32_f16 v[70:73], v[210:213], v[192:195], v[70:73]
	v_mfma_f32_16x16x32_f16 v[66:69], v[222:225], v[192:195], v[66:69]
	s_mov_b32 m0, s83
	v_lshl_add_u64 v[200:201], v[226:227], 0, s[64:65]
	s_barrier
; #define GAS __attribute__((address_space(1)))
; #define PG8_STAGE(bufoff, gbase, voff) do { _Pragma("unroll") for (int _i = 0; _i < 2; ++_i) \
;         __builtin_amdgcn_global_load_lds((const unsigned*)((const char*)(gbase) + (voff)[_i]), (LAS unsigned*)(lds + (bufoff) + ldsw + _i * 8192), 16, 0, 0); } while (0)
; #define PG8_LDA(dst, b, h) do { _Pragma("unroll") for (int m = 0; m < 4; ++m) _Pragma("unroll") for (int k = 0; k < 2; ++k) dst[m][k] = *(const LAS f16x8*)(lds + PG8_SA(b, h) + aoff + m * 2048 + k * 1024); } while (0)
; #define PG8_MMA(ai, bj, At, Bt) do { __builtin_amdgcn_s_setprio(1); _Pragma("unroll") for (int m = 0; m < 4; ++m) _Pragma("unroll") for (int n = 0; n < 2; ++n) _Pragma("unroll") for (int k = 0; k < 2; ++k) \
;         acc[ai][bj][m][n] = __builtin_amdgcn_mfma_f32_16x16x32_f16(Bt[n][k], At[m][k], acc[ai][bj][m][n], 0, 0, 0); __builtin_amdgcn_s_setprio(0); } while (0)
; #define PG8_WAIT_V(n) asm volatile("s_waitcnt vmcnt(" #n ")" ::: "memory")
; #define PG8_WAIT_L(n) asm volatile("s_waitcnt lgkmcnt(" #n ")" ::: "memory")
; #define PG8_BAR __builtin_amdgcn_s_barrier()
; #define PG8_SCHED __builtin_amdgcn_sched_barrier(0)
;     __device__ __forceinline__ void operator()(f32x4 (&acc)[2][2][4][2], const Unit& u, int wr, int wc, int fr, int fq) const {
;     ...
;         { const int lane = fr + 16 * fq, cL = u.pn * BM + wc * 32 + (lane < 32 ? lane : 96 + lane);
;           float vg = 0.f, vb = 0.f, vt = 0.f;
;           if (hasln) { vg = *(const GAS float*)(pg + cL); vb = *(const GAS float*)(pb + cL); }
;           if (haszh) vt = *(const GAS float*)(tg + cL);
; template <class Epi>
; __device__ __forceinline__ void gemm_phase(LAS unsigned char* lds, const Gemm g0, const StaticOrder& S, const Epi& E) {
;     ...
;             PG8_LDA(At, 1, 1); PG8_STAGE(PG8_SA(1, 0), a3, voffA);
;             PG8_BAR; PG8_WAIT_L(0); PG8_MMA(1, 0, At, B0); PG8_BAR; PG8_SCHED;
;             PG8_STAGE(PG8_SB(1, 1), b3 + hstep, voffB);
;             PG8_WAIT_V(6); PG8_BAR; PG8_MMA(1, 1, At, B1); PG8_BAR;
;         }
	ds_read_b128 v[146:149], v208 offset:49152
	ds_read_b128 v[150:153], v208 offset:50176
	ds_read_b128 v[154:157], v208 offset:51200
	ds_read_b128 v[162:165], v208 offset:52224
	ds_read_b128 v[170:173], v208 offset:53248
	ds_read_b128 v[184:187], v208 offset:54272
	ds_read_b128 v[188:191], v208 offset:55296
	ds_read_b128 v[192:195], v208 offset:56320
	global_load_lds_dwordx4 v[200:201], off
	v_lshl_add_u64 v[200:201], v[228:229], 0, s[64:65]
	s_mov_b32 m0, s84
	s_nop 0
	global_load_lds_dwordx4 v[200:201], off
	s_barrier
	s_waitcnt lgkmcnt(0)
	s_waitcnt lgkmcnt(0)
	v_mfma_f32_16x16x32_f16 v[62:65], v[130:133], v[146:149], v[62:65]
	v_mfma_f32_16x16x32_f16 v[58:61], v[138:141], v[146:149], v[58:61]
	v_mfma_f32_16x16x32_f16 v[46:49], v[130:133], v[154:157], v[46:49]
	v_mfma_f32_16x16x32_f16 v[42:45], v[138:141], v[154:157], v[42:45]
	v_mfma_f32_16x16x32_f16 v[30:33], v[130:133], v[170:173], v[30:33]
	v_mfma_f32_16x16x32_f16 v[26:29], v[138:141], v[170:173], v[26:29]
	v_mfma_f32_16x16x32_f16 v[14:17], v[130:133], v[188:191], v[14:17]
	v_mfma_f32_16x16x32_f16 v[10:13], v[138:141], v[188:191], v[10:13]
	v_mfma_f32_16x16x32_f16 v[62:65], v[134:137], v[150:153], v[62:65]
	v_mfma_f32_16x16x32_f16 v[58:61], v[142:145], v[150:153], v[58:61]
	v_mfma_f32_16x16x32_f16 v[46:49], v[134:137], v[162:165], v[46:49]
	v_mfma_f32_16x16x32_f16 v[42:45], v[142:145], v[162:165], v[42:45]
	v_mfma_f32_16x16x32_f16 v[30:33], v[134:137], v[184:187], v[30:33]
	v_mfma_f32_16x16x32_f16 v[26:29], v[142:145], v[184:187], v[26:29]
	v_mfma_f32_16x16x32_f16 v[14:17], v[134:137], v[192:195], v[14:17]
	v_mfma_f32_16x16x32_f16 v[10:13], v[142:145], v[192:195], v[10:13]
	s_barrier
	s_add_u32 s12, s62, 0x160080
	s_addc_u32 s13, s63, 0
	s_add_i32 s23, s80, s19
	s_mov_b32 m0, s23
	s_nop 0
	global_load_lds_dwordx4 v174, s[12:13]
	s_add_i32 m0, s23, 0x2000
	s_nop 0
	global_load_lds_dwordx4 v158, s[12:13]
	s_waitcnt vmcnt(6)
	s_barrier
	v_mfma_f32_16x16x32_f16 v[54:57], v[196:199], v[146:149], v[54:57]
	v_mfma_f32_16x16x32_f16 v[50:53], v[214:217], v[146:149], v[50:53]
	v_mfma_f32_16x16x32_f16 v[38:41], v[196:199], v[154:157], v[38:41]
	v_mfma_f32_16x16x32_f16 v[34:37], v[214:217], v[154:157], v[34:37]
	v_mfma_f32_16x16x32_f16 v[22:25], v[196:199], v[170:173], v[22:25]
	v_mfma_f32_16x16x32_f16 v[18:21], v[214:217], v[170:173], v[18:21]
	v_mfma_f32_16x16x32_f16 v[6:9], v[196:199], v[188:191], v[6:9]
	v_mfma_f32_16x16x32_f16 v[2:5], v[214:217], v[188:191], v[2:5]
	v_mfma_f32_16x16x32_f16 v[54:57], v[210:213], v[150:153], v[54:57]
	v_mfma_f32_16x16x32_f16 v[50:53], v[222:225], v[150:153], v[50:53]
	v_mfma_f32_16x16x32_f16 v[38:41], v[210:213], v[162:165], v[38:41]
	v_mfma_f32_16x16x32_f16 v[34:37], v[222:225], v[162:165], v[34:37]
	v_mfma_f32_16x16x32_f16 v[22:25], v[210:213], v[184:187], v[22:25]
	v_mfma_f32_16x16x32_f16 v[18:21], v[222:225], v[184:187], v[18:21]
	v_mfma_f32_16x16x32_f16 v[6:9], v[210:213], v[192:195], v[6:9]
	v_mfma_f32_16x16x32_f16 v[2:5], v[222:225], v[192:195], v[2:5]
	s_add_i32 s22, s22, 2
	s_add_u32 s24, s24, 0x100
	s_addc_u32 s25, s25, 0
	s_cmpk_gt_u32 s22, 0x55
	s_mov_b64 s[12:13], s[10:11]
	s_barrier
	s_cbranch_scc0 .LBB0_672
	s_lshl_b32 s10, s92, 8
	s_or_b32 s12, s10, s82
	v_add_u32_e32 v130, s12, v204
	v_ashrrev_i32_e32 v131, 31, v130
	v_lshlrev_b64 v[132:133], 2, v[130:131]
	v_lshl_add_u64 v[134:135], s[38:39], 0, v[132:133]
	v_lshl_add_u64 v[132:133], s[48:49], 0, v[132:133]
	global_load_dword v146, v[134:135], off
	global_load_dword v147, v[132:133], off
	v_readlane_b32 s22, v254, 55
	v_readlane_b32 s23, v254, 56
	s_andn2_b64 vcc, exec, s[22:23]
	v_mov_b32_e32 v148, 0
	v_cndmask_b32_e64 v132, 0, 1, s[22:23]
	v_cmp_ne_u32_e64 s[10:11], 1, v132
	s_cbranch_vccnz .LBB0_675
	v_lshl_add_u64 v[130:131], v[130:131], 2, s[50:51]
	global_load_dword v148, v[130:131], off
